# v11 + P4 EpiIn f32 K/V nt stores regrouped via permlane16_swap into 32-B contiguous pieces
# speedup vs baseline: 1.0015x; 1.0015x over previous
; #define GASP __attribute__((address_space(1)))
; template <bool PERM>
; __device__ __forceinline__ void ln_fold_fix(Acc& acc, const Unit& u, int wr, int wc, int fr, int fq, const float* c1, const float* c2, LAS unsigned char* lds) {
;     ...
;         for (int n = 0; n < 2; ++n) { const int c = u.pn * BM + bj * HALF + wc * 32 + (PERM ? 8 * fq + 4 * n : 16 * n + 4 * fq);
;             const f32x4 a1 = *(const GASP f32x4*)(c1 + c), a2 = *(const GASP f32x4*)(c2 + c);
; #pragma unroll
;             for (int ai = 0; ai < 2; ++ai)
; #pragma unroll
;                 for (int m = 0; m < 4; ++m) { const f32x2 st = SL[ai * HALF + wr * 64 + m * 16 + fr]; acc[ai][bj][m][n] = (acc[ai][bj][m][n] - a1 * st[0]) * st[1] + a2; } }
;     __device__ __forceinline__ void operator()(Acc& acc, const Unit& u, int wr, int wc, int fr, int fq, LAS unsigned char* lds) const {
;     ...
;                     f32x4 v0 = acc[ai][bj][m][0], v1 = acc[ai][bj][m][1];
;                     const size_t o = (size_t)row * 512 + col0 + bj * HALF;
;                     if (sec == 0) { v0 = v0 * qscale; v1 = v1 * qscale; }
;                     if (sec == 1) { float* of = (row < NP ? out + OUT_KP + (size_t)row * 512 : out + OUT_KS + (size_t)(row - NP) * 512) + col0 + bj * HALF; __builtin_nontemporal_store(v0, (GASP f32x4*)of); __builtin_nontemporal_store(v1, (GASP f32x4*)(of + 4)); }
;                     if (sec == 2) { float* of = (row < NP ? out + OUT_VP + (size_t)row * 512 : out + OUT_VS + (size_t)(row - NP) * 512) + col0 + bj * HALF; __builtin_nontemporal_store(v0, (GASP f32x4*)of); __builtin_nontemporal_store(v1, (GASP f32x4*)(of + 4)); }
.LBB0_422:
	s_or_b64 exec, exec, s[14:15]
	s_lshl_b32 s12, s24, 8
	s_or_b32 s5, s12, s30
	v_or_b32_e32 v32, s5, v215
	v_ashrrev_i32_e32 v33, 31, v32
	v_lshlrev_b64 v[32:33], 2, v[32:33]
	s_waitcnt lgkmcnt(0)
	s_barrier
	v_lshl_add_u64 v[34:35], s[60:61], 0, v[32:33]
	global_load_dwordx4 v[52:55], v[34:35], off offset:16
	global_load_dwordx4 v[60:63], v[34:35], off
	v_lshl_add_u64 v[32:33], s[62:63], 0, v[32:33]
	global_load_dwordx4 v[56:59], v[32:33], off offset:16
	global_load_dwordx4 v[64:67], v[32:33], off
	ds_read2_b64 v[156:159], v224 offset1:16
	s_bitset1_b32 s5, 7
	v_or_b32_e32 v40, s5, v218
	v_ashrrev_i32_e32 v41, 31, v40
	v_lshl_add_u64 v[40:41], v[40:41], 2, s[60:61]
	s_and_b32 s12, s12, 0x100
	v_or_b32_e32 v226, s12, v219
	v_add_u32_e32 v200, v168, v214
	v_ashrrev_i32_e32 v201, 31, v200
	v_add_u32_e32 v188, 0xffff8000, v200
	v_lshlrev_b64 v[202:203], 9, v[200:201]
	v_lshlrev_b64 v[176:177], 11, v[188:189]
	v_cmp_gt_i32_e64 s[18:19], s51, v200
	s_waitcnt vmcnt(0) lgkmcnt(0)
	v_pk_fma_f32 v[28:29], v[156:157], v[52:53], v[28:29] op_sel_hi:[0,1,1] neg_lo:[1,0,0] neg_hi:[1,0,0]
	v_xor_b32_e32 v199, 0x80000000, v63
	v_pk_fma_f32 v[204:205], v[156:157], v[28:29], v[56:57] op_sel:[1,0,0]
	v_or_b32_e32 v28, s5, v215
	v_ashrrev_i32_e32 v29, 31, v28
	v_xor_b32_e32 v198, 0x80000000, v62
	v_pk_fma_f32 v[30:31], v[156:157], v[54:55], v[30:31] op_sel_hi:[0,1,1] neg_lo:[1,0,0] neg_hi:[1,0,0]
	v_lshlrev_b64 v[28:29], 2, v[28:29]
	v_pk_fma_f32 v[26:27], v[198:199], v[156:157], v[26:27] op_sel_hi:[1,0,1]
	v_pk_fma_f32 v[24:25], v[60:61], v[156:157], v[24:25] op_sel_hi:[1,0,1] neg_lo:[1,0,0] neg_hi:[1,0,0]
	v_pk_fma_f32 v[178:179], v[156:157], v[30:31], v[58:59] op_sel:[1,0,0]
	v_lshl_add_u64 v[30:31], s[60:61], 0, v[28:29]
	v_lshl_add_u64 v[32:33], s[62:63], 0, v[28:29]
	v_pk_fma_f32 v[62:63], v[156:157], v[26:27], v[66:67] op_sel:[1,0,0]
	v_pk_fma_f32 v[170:171], v[156:157], v[24:25], v[64:65] op_sel:[1,0,0]
	ds_read2_b64 v[124:127], v224 offset0:32 offset1:48
	ds_read2_b64 v[92:95], v224 offset0:128 offset1:144
	ds_read2_b64 v[24:27], v224 offset0:160 offset1:176
	global_load_dwordx4 v[36:39], v[30:31], off
	s_nop 0
	global_load_dwordx4 v[28:31], v[32:33], off offset:16
	s_nop 0
	global_load_dwordx4 v[32:35], v[32:33], off
	s_ashr_i32 s5, s24, 1
	global_load_dwordx4 v[40:43], v[40:41], off
	s_cmp_lt_u32 s24, 2
	s_cselect_b64 s[12:13], -1, 0
	s_cmp_gt_u32 s24, 1
	s_cselect_b64 s[20:21], -1, 0
	s_cmp_eq_u32 s5, 1
	s_cselect_b64 s[16:17], -1, 0
	s_cmp_lg_u32 s5, 1
	s_cselect_b64 s[88:89], -1, 0
	v_pk_mul_f32 v[168:169], v[62:63], s[78:79] op_sel_hi:[1,0]
	v_pk_mul_f32 v[172:173], v[170:171], s[78:79] op_sel_hi:[1,0]
	v_pk_mul_f32 v[206:207], v[178:179], s[78:79] op_sel_hi:[1,0]
	v_pk_mul_f32 v[210:211], v[204:205], s[78:79] op_sel_hi:[1,0]
	v_cndmask_b32_e64 v175, v63, v169, s[12:13]
	v_cndmask_b32_e64 v174, v62, v168, s[12:13]
	v_cndmask_b32_e64 v173, v171, v173, s[12:13]
	v_cndmask_b32_e64 v172, v170, v172, s[12:13]
	v_cndmask_b32_e64 v171, v179, v207, s[12:13]
	v_cndmask_b32_e64 v170, v178, v206, s[12:13]
	v_cndmask_b32_e64 v169, v205, v211, s[12:13]
	v_cndmask_b32_e64 v168, v204, v210, s[12:13]
	s_and_b64 vcc, exec, s[88:89]
	v_lshl_add_u64 v[204:205], s[72:73], 0, v[176:177]
	v_lshl_add_u64 v[206:207], v[202:203], 2, s[70:71]
	v_lshlrev_b32_e32 v62, 2, v226
	s_cbranch_vccnz .LBB0_424
	v_cndmask_b32_e64 v179, v205, v207, s[18:19]
	v_cndmask_b32_e64 v178, v204, v206, s[18:19]
	v_mov_b32_e32 v63, v189
	v_lshl_add_u64 v[178:179], v[178:179], 0, v[62:63]
	v_mbcnt_lo_u32_b32 v238, -1, 0
	v_mbcnt_hi_u32_b32 v238, -1, v238
	v_bfe_i32 v238, v238, 4, 1
	v_lshlrev_b32_e32 v238, 4, v238
	v_ashrrev_i32_e32 v239, 31, v238
	v_lshl_add_u64 v[236:237], v[178:179], 0, v[238:239]
	v_permlane16_swap_b32_e32 v172, v168
	v_permlane16_swap_b32_e32 v173, v169
	v_permlane16_swap_b32_e32 v174, v170
	v_permlane16_swap_b32_e32 v175, v171
	global_store_dwordx4 v[236:237], v[172:175], off nt
	global_store_dwordx4 v[236:237], v[168:171], off offset:32 nt
	s_nop 1
	v_permlane16_swap_b32_e32 v172, v168
	v_permlane16_swap_b32_e32 v173, v169
	v_permlane16_swap_b32_e32 v174, v170
	v_permlane16_swap_b32_e32 v175, v171
.LBB0_424:
	s_cmp_eq_u32 s5, 2
	s_cselect_b64 s[22:23], -1, 0
	s_cmp_lg_u32 s5, 2
	s_cselect_b64 s[90:91], -1, 0
	s_and_b64 vcc, exec, s[90:91]
	v_lshl_add_u64 v[210:211], s[76:77], 0, v[176:177]
	v_lshl_add_u64 v[212:213], v[202:203], 2, s[74:75]
	s_cbranch_vccnz .LBB0_426
	v_cndmask_b32_e64 v177, v211, v213, s[18:19]
	v_cndmask_b32_e64 v176, v210, v212, s[18:19]
	v_mov_b32_e32 v63, v189
	v_lshl_add_u64 v[176:177], v[176:177], 0, v[62:63]
	v_mbcnt_lo_u32_b32 v238, -1, 0
	v_mbcnt_hi_u32_b32 v238, -1, v238
	v_bfe_i32 v238, v238, 4, 1
	v_lshlrev_b32_e32 v238, 4, v238
	v_ashrrev_i32_e32 v239, 31, v238
	v_lshl_add_u64 v[236:237], v[176:177], 0, v[238:239]
	v_permlane16_swap_b32_e32 v172, v168
	v_permlane16_swap_b32_e32 v173, v169
	v_permlane16_swap_b32_e32 v174, v170
	v_permlane16_swap_b32_e32 v175, v171
	global_store_dwordx4 v[236:237], v[172:175], off nt
	global_store_dwordx4 v[236:237], v[168:171], off offset:32 nt
	s_nop 1
	v_permlane16_swap_b32_e32 v172, v168
	v_permlane16_swap_b32_e32 v173, v169
	v_permlane16_swap_b32_e32 v174, v170
	v_permlane16_swap_b32_e32 v175, v171

; #define GASP __attribute__((address_space(1)))
; template <bool PERM>
; __device__ __forceinline__ void ln_fold_fix(Acc& acc, const Unit& u, int wr, int wc, int fr, int fq, const float* c1, const float* c2, LAS unsigned char* lds) {
;     ...
;         for (int n = 0; n < 2; ++n) { const int c = u.pn * BM + bj * HALF + wc * 32 + (PERM ? 8 * fq + 4 * n : 16 * n + 4 * fq);
;             const f32x4 a1 = *(const GASP f32x4*)(c1 + c), a2 = *(const GASP f32x4*)(c2 + c);
; #pragma unroll
;             for (int ai = 0; ai < 2; ++ai)
; #pragma unroll
;                 for (int m = 0; m < 4; ++m) { const f32x2 st = SL[ai * HALF + wr * 64 + m * 16 + fr]; acc[ai][bj][m][n] = (acc[ai][bj][m][n] - a1 * st[0]) * st[1] + a2; } }
;     __device__ __forceinline__ void operator()(Acc& acc, const Unit& u, int wr, int wc, int fr, int fq, LAS unsigned char* lds) const {
;     ...
;                     f32x4 v0 = acc[ai][bj][m][0], v1 = acc[ai][bj][m][1];
;                     const size_t o = (size_t)row * 512 + col0 + bj * HALF;
;                     if (sec == 0) { v0 = v0 * qscale; v1 = v1 * qscale; }
;                     if (sec == 1) { float* of = (row < NP ? out + OUT_KP + (size_t)row * 512 : out + OUT_KS + (size_t)(row - NP) * 512) + col0 + bj * HALF; __builtin_nontemporal_store(v0, (GASP f32x4*)of); __builtin_nontemporal_store(v1, (GASP f32x4*)(of + 4)); }
;                     if (sec == 2) { float* of = (row < NP ? out + OUT_VP + (size_t)row * 512 : out + OUT_VS + (size_t)(row - NP) * 512) + col0 + bj * HALF; __builtin_nontemporal_store(v0, (GASP f32x4*)of); __builtin_nontemporal_store(v1, (GASP f32x4*)(of + 4)); }
.LBB0_447:
	v_xor_b32_e32 v174, 0x80000000, v156
	v_mov_b32_e32 v168, v156
	v_mov_b32_e32 v169, v156
	v_mov_b32_e32 v175, v174
	v_mov_b32_e32 v170, v157
	v_mov_b32_e32 v171, v157
	s_waitcnt vmcnt(3)
	v_pk_fma_f32 v[164:165], v[168:169], v[36:37], v[164:165] neg_lo:[1,0,0] neg_hi:[1,0,0]
	v_pk_fma_f32 v[166:167], v[174:175], v[38:39], v[166:167]
	v_mov_b32_e32 v156, v157
	s_waitcnt vmcnt(0)
	v_pk_fma_f32 v[160:161], v[168:169], v[40:41], v[160:161] neg_lo:[1,0,0] neg_hi:[1,0,0]
	v_pk_fma_f32 v[162:163], v[174:175], v[42:43], v[162:163]
	v_pk_fma_f32 v[166:167], v[156:157], v[166:167], v[34:35]
	v_pk_fma_f32 v[164:165], v[170:171], v[164:165], v[32:33]
	v_pk_fma_f32 v[156:157], v[156:157], v[162:163], v[30:31]
	v_pk_fma_f32 v[160:161], v[170:171], v[160:161], v[28:29]
	v_pk_mul_f32 v[162:163], v[166:167], s[78:79] op_sel_hi:[1,0]
	v_pk_mul_f32 v[168:169], v[164:165], s[78:79] op_sel_hi:[1,0]
	v_pk_mul_f32 v[170:171], v[156:157], s[78:79] op_sel_hi:[1,0]
	v_pk_mul_f32 v[174:175], v[160:161], s[78:79] op_sel_hi:[1,0]
	v_cndmask_b32_e64 v63, 0, 1, s[16:17]
	v_cndmask_b32_e64 v165, v165, v169, s[12:13]
	v_cndmask_b32_e64 v164, v164, v168, s[12:13]
	v_cndmask_b32_e64 v167, v167, v163, s[12:13]
	v_cndmask_b32_e64 v166, v166, v162, s[12:13]
	v_cndmask_b32_e64 v161, v161, v175, s[12:13]
	v_cndmask_b32_e64 v160, v160, v174, s[12:13]
	v_cndmask_b32_e64 v163, v157, v171, s[12:13]
	v_cmp_ne_u32_e64 s[14:15], 1, v63
	s_andn2_b64 vcc, exec, s[16:17]
	v_cndmask_b32_e64 v162, v156, v170, s[12:13]
	s_cbranch_vccnz .LBB0_477
	v_cndmask_b32_e64 v157, v205, v207, s[18:19]
	v_cndmask_b32_e64 v156, v204, v206, s[18:19]
	v_mov_b32_e32 v63, v189
	v_lshl_add_u64 v[156:157], v[156:157], 0, v[62:63]
	v_mbcnt_lo_u32_b32 v238, -1, 0
	v_mbcnt_hi_u32_b32 v238, -1, v238
	v_bfe_i32 v238, v238, 4, 1
	v_lshlrev_b32_e32 v238, 4, v238
	v_ashrrev_i32_e32 v239, 31, v238
	v_lshl_add_u64 v[236:237], v[156:157], 0, v[238:239]
	v_permlane16_swap_b32_e32 v164, v160
	v_permlane16_swap_b32_e32 v165, v161
	v_permlane16_swap_b32_e32 v166, v162
	v_permlane16_swap_b32_e32 v167, v163
	global_store_dwordx4 v[236:237], v[164:167], off offset:512 nt
	global_store_dwordx4 v[236:237], v[160:163], off offset:544 nt
	s_nop 1
	v_permlane16_swap_b32_e32 v164, v160
	v_permlane16_swap_b32_e32 v165, v161
	v_permlane16_swap_b32_e32 v166, v162
	v_permlane16_swap_b32_e32 v167, v163
	v_cndmask_b32_e64 v63, 0, 1, s[22:23]
	v_cmp_ne_u32_e64 s[16:17], 1, v63
	s_andn2_b64 vcc, exec, s[22:23]
	s_cbranch_vccz .LBB0_478

; #define GASP __attribute__((address_space(1)))
; template <bool PERM>
; __device__ __forceinline__ void ln_fold_fix(Acc& acc, const Unit& u, int wr, int wc, int fr, int fq, const float* c1, const float* c2, LAS unsigned char* lds) {
;     ...
;         for (int n = 0; n < 2; ++n) { const int c = u.pn * BM + bj * HALF + wc * 32 + (PERM ? 8 * fq + 4 * n : 16 * n + 4 * fq);
;             const f32x4 a1 = *(const GASP f32x4*)(c1 + c), a2 = *(const GASP f32x4*)(c2 + c);
; #pragma unroll
;             for (int ai = 0; ai < 2; ++ai)
; #pragma unroll
;                 for (int m = 0; m < 4; ++m) { const f32x2 st = SL[ai * HALF + wr * 64 + m * 16 + fr]; acc[ai][bj][m][n] = (acc[ai][bj][m][n] - a1 * st[0]) * st[1] + a2; } }
;     __device__ __forceinline__ void operator()(Acc& acc, const Unit& u, int wr, int wc, int fr, int fq, LAS unsigned char* lds) const {
;     ...
;                     f32x4 v0 = acc[ai][bj][m][0], v1 = acc[ai][bj][m][1];
;                     const size_t o = (size_t)row * 512 + col0 + bj * HALF;
;                     if (sec == 0) { v0 = v0 * qscale; v1 = v1 * qscale; }
;                     if (sec == 1) { float* of = (row < NP ? out + OUT_KP + (size_t)row * 512 : out + OUT_KS + (size_t)(row - NP) * 512) + col0 + bj * HALF; __builtin_nontemporal_store(v0, (GASP f32x4*)of); __builtin_nontemporal_store(v1, (GASP f32x4*)(of + 4)); }
;                     if (sec == 2) { float* of = (row < NP ? out + OUT_VP + (size_t)row * 512 : out + OUT_VS + (size_t)(row - NP) * 512) + col0 + bj * HALF; __builtin_nontemporal_store(v0, (GASP f32x4*)of); __builtin_nontemporal_store(v1, (GASP f32x4*)(of + 4)); }
.LBB0_471:
	v_pk_fma_f32 v[152:153], v[60:61], v[158:159], v[152:153] op_sel_hi:[1,0,1] neg_lo:[1,0,0] neg_hi:[1,0,0]
	v_pk_fma_f32 v[154:155], v[198:199], v[158:159], v[154:155] op_sel_hi:[1,0,1]
	v_pk_fma_f32 v[148:149], v[158:159], v[52:53], v[148:149] op_sel_hi:[0,1,1] neg_lo:[1,0,0] neg_hi:[1,0,0]
	v_pk_fma_f32 v[150:151], v[158:159], v[54:55], v[150:151] op_sel_hi:[0,1,1] neg_lo:[1,0,0] neg_hi:[1,0,0]
	v_or_b32_e32 v156, 16, v200
	v_pk_fma_f32 v[154:155], v[158:159], v[154:155], v[66:67] op_sel:[1,0,0]
	v_pk_fma_f32 v[152:153], v[158:159], v[152:153], v[64:65] op_sel:[1,0,0]
	v_pk_fma_f32 v[150:151], v[158:159], v[150:151], v[58:59] op_sel:[1,0,0]
	v_pk_fma_f32 v[148:149], v[158:159], v[148:149], v[56:57] op_sel:[1,0,0]
	v_ashrrev_i32_e32 v157, 31, v156
	v_add_u32_e32 v188, 0xffff8010, v200
	v_lshlrev_b64 v[164:165], 9, v[156:157]
	s_waitcnt lgkmcnt(0)
	v_lshlrev_b64 v[160:161], 11, v[188:189]
	v_pk_mul_f32 v[162:163], v[154:155], s[78:79] op_sel_hi:[1,0]
	v_pk_mul_f32 v[166:167], v[152:153], s[78:79] op_sel_hi:[1,0]
	v_pk_mul_f32 v[168:169], v[150:151], s[78:79] op_sel_hi:[1,0]
	v_pk_mul_f32 v[170:171], v[148:149], s[78:79] op_sel_hi:[1,0]
	v_cmp_gt_i32_e64 s[26:27], s51, v156
	v_cndmask_b32_e64 v153, v153, v167, s[12:13]
	v_cndmask_b32_e64 v152, v152, v166, s[12:13]
	v_cndmask_b32_e64 v155, v155, v163, s[12:13]
	v_cndmask_b32_e64 v154, v154, v162, s[12:13]
	v_cndmask_b32_e64 v149, v149, v171, s[12:13]
	v_cndmask_b32_e64 v148, v148, v170, s[12:13]
	v_cndmask_b32_e64 v151, v151, v169, s[12:13]
	v_cndmask_b32_e64 v150, v150, v168, s[12:13]
	s_and_b64 vcc, exec, s[14:15]
	v_lshl_add_u64 v[166:167], s[72:73], 0, v[160:161]
	v_lshl_add_u64 v[168:169], v[164:165], 2, s[70:71]
	s_cbranch_vccnz .LBB0_479
	v_cndmask_b32_e64 v163, v167, v169, s[26:27]
	v_cndmask_b32_e64 v162, v166, v168, s[26:27]
	v_mov_b32_e32 v63, v189
	v_lshl_add_u64 v[162:163], v[162:163], 0, v[62:63]
	v_mbcnt_lo_u32_b32 v238, -1, 0
	v_mbcnt_hi_u32_b32 v238, -1, v238
	v_bfe_i32 v238, v238, 4, 1
	v_lshlrev_b32_e32 v238, 4, v238
	v_ashrrev_i32_e32 v239, 31, v238
	v_lshl_add_u64 v[236:237], v[162:163], 0, v[238:239]
	v_permlane16_swap_b32_e32 v152, v148
	v_permlane16_swap_b32_e32 v153, v149
	v_permlane16_swap_b32_e32 v154, v150
	v_permlane16_swap_b32_e32 v155, v151
	global_store_dwordx4 v[236:237], v[152:155], off nt
	global_store_dwordx4 v[236:237], v[148:151], off offset:32 nt
	s_nop 1
	v_permlane16_swap_b32_e32 v152, v148
	v_permlane16_swap_b32_e32 v153, v149
	v_permlane16_swap_b32_e32 v154, v150
	v_permlane16_swap_b32_e32 v155, v151
	s_and_b64 vcc, exec, s[16:17]
	v_lshl_add_u64 v[170:171], s[76:77], 0, v[160:161]
	v_lshl_add_u64 v[172:173], v[164:165], 2, s[74:75]
	s_cbranch_vccz .LBB0_480

; #define GASP __attribute__((address_space(1)))
;     __device__ __forceinline__ void operator()(Acc& acc, const Unit& u, int wr, int wc, int fr, int fq, LAS unsigned char* lds) const {
;     ...
;                     f32x4 v0 = acc[ai][bj][m][0], v1 = acc[ai][bj][m][1];
;                     const size_t o = (size_t)row * 512 + col0 + bj * HALF;
;                     if (sec == 0) { v0 = v0 * qscale; v1 = v1 * qscale; }
;                     if (sec == 1) { float* of = (row < NP ? out + OUT_KP + (size_t)row * 512 : out + OUT_KS + (size_t)(row - NP) * 512) + col0 + bj * HALF; __builtin_nontemporal_store(v0, (GASP f32x4*)of); __builtin_nontemporal_store(v1, (GASP f32x4*)(of + 4)); }
;                     if (sec == 2) { float* of = (row < NP ? out + OUT_VP + (size_t)row * 512 : out + OUT_VS + (size_t)(row - NP) * 512) + col0 + bj * HALF; __builtin_nontemporal_store(v0, (GASP f32x4*)of); __builtin_nontemporal_store(v1, (GASP f32x4*)(of + 4)); }
.LBB0_478:
	v_cndmask_b32_e64 v157, v211, v213, s[18:19]
	v_cndmask_b32_e64 v156, v210, v212, s[18:19]
	v_mov_b32_e32 v63, v189
	v_lshl_add_u64 v[156:157], v[156:157], 0, v[62:63]
	v_mbcnt_lo_u32_b32 v238, -1, 0
	v_mbcnt_hi_u32_b32 v238, -1, v238
	v_bfe_i32 v238, v238, 4, 1
	v_lshlrev_b32_e32 v238, 4, v238
	v_ashrrev_i32_e32 v239, 31, v238
	v_lshl_add_u64 v[236:237], v[156:157], 0, v[238:239]
	v_permlane16_swap_b32_e32 v164, v160
	v_permlane16_swap_b32_e32 v165, v161
	v_permlane16_swap_b32_e32 v166, v162
	v_permlane16_swap_b32_e32 v167, v163
	global_store_dwordx4 v[236:237], v[164:167], off offset:512 nt
	global_store_dwordx4 v[236:237], v[160:163], off offset:544 nt
	s_nop 1
	v_permlane16_swap_b32_e32 v164, v160
	v_permlane16_swap_b32_e32 v165, v161
	v_permlane16_swap_b32_e32 v166, v162
	v_permlane16_swap_b32_e32 v167, v163
	v_cndmask_b32_e64 v63, 0, 1, s[94:95]
	v_cmp_ne_u32_e64 s[18:19], 1, v63
	s_andn2_b64 vcc, exec, s[94:95]
	s_cbranch_vccz .LBB0_450
	s_branch .LBB0_451

; #define GASP __attribute__((address_space(1)))
;     __device__ __forceinline__ void operator()(Acc& acc, const Unit& u, int wr, int wc, int fr, int fq, LAS unsigned char* lds) const {
;     ...
;                     f32x4 v0 = acc[ai][bj][m][0], v1 = acc[ai][bj][m][1];
;                     const size_t o = (size_t)row * 512 + col0 + bj * HALF;
;                     if (sec == 0) { v0 = v0 * qscale; v1 = v1 * qscale; }
;                     if (sec == 1) { float* of = (row < NP ? out + OUT_KP + (size_t)row * 512 : out + OUT_KS + (size_t)(row - NP) * 512) + col0 + bj * HALF; __builtin_nontemporal_store(v0, (GASP f32x4*)of); __builtin_nontemporal_store(v1, (GASP f32x4*)(of + 4)); }
;                     if (sec == 2) { float* of = (row < NP ? out + OUT_VP + (size_t)row * 512 : out + OUT_VS + (size_t)(row - NP) * 512) + col0 + bj * HALF; __builtin_nontemporal_store(v0, (GASP f32x4*)of); __builtin_nontemporal_store(v1, (GASP f32x4*)(of + 4)); }
.LBB0_480:
	v_cndmask_b32_e64 v161, v171, v173, s[26:27]
	v_cndmask_b32_e64 v160, v170, v172, s[26:27]
	v_mov_b32_e32 v63, v189
	v_lshl_add_u64 v[160:161], v[160:161], 0, v[62:63]
	v_mbcnt_lo_u32_b32 v238, -1, 0
	v_mbcnt_hi_u32_b32 v238, -1, v238
	v_bfe_i32 v238, v238, 4, 1
	v_lshlrev_b32_e32 v238, 4, v238
	v_ashrrev_i32_e32 v239, 31, v238
	v_lshl_add_u64 v[236:237], v[160:161], 0, v[238:239]
	v_permlane16_swap_b32_e32 v152, v148
	v_permlane16_swap_b32_e32 v153, v149
	v_permlane16_swap_b32_e32 v154, v150
	v_permlane16_swap_b32_e32 v155, v151
	global_store_dwordx4 v[236:237], v[152:155], off nt
	global_store_dwordx4 v[236:237], v[148:151], off offset:32 nt
	s_nop 1
	v_permlane16_swap_b32_e32 v152, v148
	v_permlane16_swap_b32_e32 v153, v149
	v_permlane16_swap_b32_e32 v154, v150
	v_permlane16_swap_b32_e32 v155, v151
	s_and_b64 vcc, exec, s[18:19]
	s_cbranch_vccz .LBB0_474

; #define GASP __attribute__((address_space(1)))
; template <bool PERM>
; __device__ __forceinline__ void ln_fold_fix(Acc& acc, const Unit& u, int wr, int wc, int fr, int fq, const float* c1, const float* c2, LAS unsigned char* lds) {
;     ...
;         for (int n = 0; n < 2; ++n) { const int c = u.pn * BM + bj * HALF + wc * 32 + (PERM ? 8 * fq + 4 * n : 16 * n + 4 * fq);
;             const f32x4 a1 = *(const GASP f32x4*)(c1 + c), a2 = *(const GASP f32x4*)(c2 + c);
; #pragma unroll
;             for (int ai = 0; ai < 2; ++ai)
; #pragma unroll
;                 for (int m = 0; m < 4; ++m) { const f32x2 st = SL[ai * HALF + wr * 64 + m * 16 + fr]; acc[ai][bj][m][n] = (acc[ai][bj][m][n] - a1 * st[0]) * st[1] + a2; } }
;     __device__ __forceinline__ void operator()(Acc& acc, const Unit& u, int wr, int wc, int fr, int fq, LAS unsigned char* lds) const {
;     ...
;                     f32x4 v0 = acc[ai][bj][m][0], v1 = acc[ai][bj][m][1];
;                     const size_t o = (size_t)row * 512 + col0 + bj * HALF;
;                     if (sec == 0) { v0 = v0 * qscale; v1 = v1 * qscale; }
;                     if (sec == 1) { float* of = (row < NP ? out + OUT_KP + (size_t)row * 512 : out + OUT_KS + (size_t)(row - NP) * 512) + col0 + bj * HALF; __builtin_nontemporal_store(v0, (GASP f32x4*)of); __builtin_nontemporal_store(v1, (GASP f32x4*)(of + 4)); }
;                     if (sec == 2) { float* of = (row < NP ? out + OUT_VP + (size_t)row * 512 : out + OUT_VS + (size_t)(row - NP) * 512) + col0 + bj * HALF; __builtin_nontemporal_store(v0, (GASP f32x4*)of); __builtin_nontemporal_store(v1, (GASP f32x4*)(of + 4)); }
.LBB0_496:
	v_xor_b32_e32 v154, 0x80000000, v158
	v_mov_b32_e32 v148, v158
	v_mov_b32_e32 v149, v158
	v_mov_b32_e32 v155, v154
	v_mov_b32_e32 v150, v159
	v_mov_b32_e32 v151, v159
	v_pk_fma_f32 v[144:145], v[148:149], v[36:37], v[144:145] neg_lo:[1,0,0] neg_hi:[1,0,0]
	v_pk_fma_f32 v[146:147], v[154:155], v[38:39], v[146:147]
	v_mov_b32_e32 v158, v159
	v_pk_fma_f32 v[140:141], v[148:149], v[40:41], v[140:141] neg_lo:[1,0,0] neg_hi:[1,0,0]
	v_pk_fma_f32 v[142:143], v[154:155], v[42:43], v[142:143]
	v_pk_fma_f32 v[146:147], v[158:159], v[146:147], v[34:35]
	v_pk_fma_f32 v[144:145], v[150:151], v[144:145], v[32:33]
	v_pk_fma_f32 v[142:143], v[158:159], v[142:143], v[30:31]
	v_pk_fma_f32 v[140:141], v[150:151], v[140:141], v[28:29]
	v_pk_mul_f32 v[148:149], v[146:147], s[78:79] op_sel_hi:[1,0]
	v_pk_mul_f32 v[150:151], v[144:145], s[78:79] op_sel_hi:[1,0]
	v_pk_mul_f32 v[154:155], v[142:143], s[78:79] op_sel_hi:[1,0]
	v_pk_mul_f32 v[158:159], v[140:141], s[78:79] op_sel_hi:[1,0]
	v_cndmask_b32_e64 v145, v145, v151, s[12:13]
	v_cndmask_b32_e64 v144, v144, v150, s[12:13]
	v_cndmask_b32_e64 v147, v147, v149, s[12:13]
	v_cndmask_b32_e64 v146, v146, v148, s[12:13]
	v_cndmask_b32_e64 v141, v141, v159, s[12:13]
	v_cndmask_b32_e64 v140, v140, v158, s[12:13]
	v_cndmask_b32_e64 v143, v143, v155, s[12:13]
	s_and_b64 vcc, exec, s[14:15]
	v_cndmask_b32_e64 v142, v142, v154, s[12:13]
	s_cbranch_vccnz .LBB0_502
	v_cndmask_b32_e64 v149, v167, v169, s[26:27]
	v_cndmask_b32_e64 v148, v166, v168, s[26:27]
	v_mov_b32_e32 v63, v189
	v_lshl_add_u64 v[148:149], v[148:149], 0, v[62:63]
	v_mbcnt_lo_u32_b32 v238, -1, 0
	v_mbcnt_hi_u32_b32 v238, -1, v238
	v_bfe_i32 v238, v238, 4, 1
	v_lshlrev_b32_e32 v238, 4, v238
	v_ashrrev_i32_e32 v239, 31, v238
	v_lshl_add_u64 v[236:237], v[148:149], 0, v[238:239]
	v_permlane16_swap_b32_e32 v144, v140
	v_permlane16_swap_b32_e32 v145, v141
	v_permlane16_swap_b32_e32 v146, v142
	v_permlane16_swap_b32_e32 v147, v143
	global_store_dwordx4 v[236:237], v[144:147], off offset:512 nt
	global_store_dwordx4 v[236:237], v[140:143], off offset:544 nt
	s_nop 1
	v_permlane16_swap_b32_e32 v144, v140
	v_permlane16_swap_b32_e32 v145, v141
	v_permlane16_swap_b32_e32 v146, v142
	v_permlane16_swap_b32_e32 v147, v143
	s_and_b64 vcc, exec, s[16:17]
	s_cbranch_vccz .LBB0_503

; #define GASP __attribute__((address_space(1)))
;     __device__ __forceinline__ void operator()(Acc& acc, const Unit& u, int wr, int wc, int fr, int fq, LAS unsigned char* lds) const {
;     ...
;                     f32x4 v0 = acc[ai][bj][m][0], v1 = acc[ai][bj][m][1];
;                     const size_t o = (size_t)row * 512 + col0 + bj * HALF;
;                     if (sec == 0) { v0 = v0 * qscale; v1 = v1 * qscale; }
;                     if (sec == 1) { float* of = (row < NP ? out + OUT_KP + (size_t)row * 512 : out + OUT_KS + (size_t)(row - NP) * 512) + col0 + bj * HALF; __builtin_nontemporal_store(v0, (GASP f32x4*)of); __builtin_nontemporal_store(v1, (GASP f32x4*)(of + 4)); }
;                     if (sec == 2) { float* of = (row < NP ? out + OUT_VP + (size_t)row * 512 : out + OUT_VS + (size_t)(row - NP) * 512) + col0 + bj * HALF; __builtin_nontemporal_store(v0, (GASP f32x4*)of); __builtin_nontemporal_store(v1, (GASP f32x4*)(of + 4)); }
.LBB0_503:
	v_cndmask_b32_e64 v149, v171, v173, s[26:27]
	v_cndmask_b32_e64 v148, v170, v172, s[26:27]
	v_mov_b32_e32 v63, v189
	v_lshl_add_u64 v[148:149], v[148:149], 0, v[62:63]
	v_mbcnt_lo_u32_b32 v238, -1, 0
	v_mbcnt_hi_u32_b32 v238, -1, v238
	v_bfe_i32 v238, v238, 4, 1
	v_lshlrev_b32_e32 v238, 4, v238
	v_ashrrev_i32_e32 v239, 31, v238
	v_lshl_add_u64 v[236:237], v[148:149], 0, v[238:239]
	v_permlane16_swap_b32_e32 v144, v140
	v_permlane16_swap_b32_e32 v145, v141
	v_permlane16_swap_b32_e32 v146, v142
	v_permlane16_swap_b32_e32 v147, v143
	global_store_dwordx4 v[236:237], v[144:147], off offset:512 nt
	global_store_dwordx4 v[236:237], v[140:143], off offset:544 nt
	s_nop 1
	v_permlane16_swap_b32_e32 v144, v140
	v_permlane16_swap_b32_e32 v145, v141
	v_permlane16_swap_b32_e32 v146, v142
	v_permlane16_swap_b32_e32 v147, v143
	s_and_b64 vcc, exec, s[18:19]
	s_cbranch_vccz .LBB0_499

; #define GASP __attribute__((address_space(1)))
; template <bool PERM>
; __device__ __forceinline__ void ln_fold_fix(Acc& acc, const Unit& u, int wr, int wc, int fr, int fq, const float* c1, const float* c2, LAS unsigned char* lds) {
;     ...
;         for (int n = 0; n < 2; ++n) { const int c = u.pn * BM + bj * HALF + wc * 32 + (PERM ? 8 * fq + 4 * n : 16 * n + 4 * fq);
;             const f32x4 a1 = *(const GASP f32x4*)(c1 + c), a2 = *(const GASP f32x4*)(c2 + c);
; #pragma unroll
;             for (int ai = 0; ai < 2; ++ai)
; #pragma unroll
;                 for (int m = 0; m < 4; ++m) { const f32x2 st = SL[ai * HALF + wr * 64 + m * 16 + fr]; acc[ai][bj][m][n] = (acc[ai][bj][m][n] - a1 * st[0]) * st[1] + a2; } }
;     __device__ __forceinline__ void operator()(Acc& acc, const Unit& u, int wr, int wc, int fr, int fq, LAS unsigned char* lds) const {
;     ...
;                     f32x4 v0 = acc[ai][bj][m][0], v1 = acc[ai][bj][m][1];
;                     const size_t o = (size_t)row * 512 + col0 + bj * HALF;
;                     if (sec == 0) { v0 = v0 * qscale; v1 = v1 * qscale; }
;                     if (sec == 1) { float* of = (row < NP ? out + OUT_KP + (size_t)row * 512 : out + OUT_KS + (size_t)(row - NP) * 512) + col0 + bj * HALF; __builtin_nontemporal_store(v0, (GASP f32x4*)of); __builtin_nontemporal_store(v1, (GASP f32x4*)(of + 4)); }
;                     if (sec == 2) { float* of = (row < NP ? out + OUT_VP + (size_t)row * 512 : out + OUT_VS + (size_t)(row - NP) * 512) + col0 + bj * HALF; __builtin_nontemporal_store(v0, (GASP f32x4*)of); __builtin_nontemporal_store(v1, (GASP f32x4*)(of + 4)); }
.LBB0_522:
	v_pk_fma_f32 v[136:137], v[60:61], v[124:125], v[136:137] op_sel_hi:[1,0,1] neg_lo:[1,0,0] neg_hi:[1,0,0]
	v_pk_fma_f32 v[138:139], v[198:199], v[124:125], v[138:139] op_sel_hi:[1,0,1]
	v_pk_fma_f32 v[132:133], v[124:125], v[52:53], v[132:133] op_sel_hi:[0,1,1] neg_lo:[1,0,0] neg_hi:[1,0,0]
	v_pk_fma_f32 v[134:135], v[124:125], v[54:55], v[134:135] op_sel_hi:[0,1,1] neg_lo:[1,0,0] neg_hi:[1,0,0]
	v_or_b32_e32 v144, 32, v200
	v_pk_fma_f32 v[138:139], v[124:125], v[138:139], v[66:67] op_sel:[1,0,0]
	v_pk_fma_f32 v[136:137], v[124:125], v[136:137], v[64:65] op_sel:[1,0,0]
	v_pk_fma_f32 v[134:135], v[124:125], v[134:135], v[58:59] op_sel:[1,0,0]
	v_pk_fma_f32 v[132:133], v[124:125], v[132:133], v[56:57] op_sel:[1,0,0]
	v_ashrrev_i32_e32 v145, 31, v144
	v_add_u32_e32 v188, 0xffff8020, v200
	v_lshlrev_b64 v[146:147], 9, v[144:145]
	v_lshlrev_b64 v[140:141], 11, v[188:189]
	s_waitcnt lgkmcnt(0)
	v_pk_mul_f32 v[142:143], v[138:139], s[78:79] op_sel_hi:[1,0]
	v_pk_mul_f32 v[148:149], v[136:137], s[78:79] op_sel_hi:[1,0]
	v_pk_mul_f32 v[150:151], v[134:135], s[78:79] op_sel_hi:[1,0]
	v_pk_mul_f32 v[152:153], v[132:133], s[78:79] op_sel_hi:[1,0]
	v_cmp_gt_i32_e64 s[26:27], s51, v144
	v_cndmask_b32_e64 v137, v137, v149, s[12:13]
	v_cndmask_b32_e64 v136, v136, v148, s[12:13]
	v_cndmask_b32_e64 v139, v139, v143, s[12:13]
	v_cndmask_b32_e64 v138, v138, v142, s[12:13]
	v_cndmask_b32_e64 v133, v133, v153, s[12:13]
	v_cndmask_b32_e64 v132, v132, v152, s[12:13]
	v_cndmask_b32_e64 v135, v135, v151, s[12:13]
	v_cndmask_b32_e64 v134, v134, v150, s[12:13]
	s_and_b64 vcc, exec, s[14:15]
	v_lshl_add_u64 v[148:149], s[72:73], 0, v[140:141]
	v_lshl_add_u64 v[150:151], v[146:147], 2, s[70:71]
	s_cbranch_vccnz .LBB0_528
	v_cndmask_b32_e64 v143, v149, v151, s[26:27]
	v_cndmask_b32_e64 v142, v148, v150, s[26:27]
	v_mov_b32_e32 v63, v189
	v_lshl_add_u64 v[142:143], v[142:143], 0, v[62:63]
	v_mbcnt_lo_u32_b32 v238, -1, 0
	v_mbcnt_hi_u32_b32 v238, -1, v238
	v_bfe_i32 v238, v238, 4, 1
	v_lshlrev_b32_e32 v238, 4, v238
	v_ashrrev_i32_e32 v239, 31, v238
	v_lshl_add_u64 v[236:237], v[142:143], 0, v[238:239]
	v_permlane16_swap_b32_e32 v136, v132
	v_permlane16_swap_b32_e32 v137, v133
	v_permlane16_swap_b32_e32 v138, v134
	v_permlane16_swap_b32_e32 v139, v135
	global_store_dwordx4 v[236:237], v[136:139], off nt
	global_store_dwordx4 v[236:237], v[132:135], off offset:32 nt
	s_nop 1
	v_permlane16_swap_b32_e32 v136, v132
	v_permlane16_swap_b32_e32 v137, v133
	v_permlane16_swap_b32_e32 v138, v134
	v_permlane16_swap_b32_e32 v139, v135
	s_and_b64 vcc, exec, s[16:17]
	v_lshl_add_u64 v[152:153], s[76:77], 0, v[140:141]
	v_lshl_add_u64 v[154:155], v[146:147], 2, s[74:75]
	s_cbranch_vccz .LBB0_529

; #define GASP __attribute__((address_space(1)))
;     __device__ __forceinline__ void operator()(Acc& acc, const Unit& u, int wr, int wc, int fr, int fq, LAS unsigned char* lds) const {
;     ...
;                     f32x4 v0 = acc[ai][bj][m][0], v1 = acc[ai][bj][m][1];
;                     const size_t o = (size_t)row * 512 + col0 + bj * HALF;
;                     if (sec == 0) { v0 = v0 * qscale; v1 = v1 * qscale; }
;                     if (sec == 1) { float* of = (row < NP ? out + OUT_KP + (size_t)row * 512 : out + OUT_KS + (size_t)(row - NP) * 512) + col0 + bj * HALF; __builtin_nontemporal_store(v0, (GASP f32x4*)of); __builtin_nontemporal_store(v1, (GASP f32x4*)(of + 4)); }
;                     if (sec == 2) { float* of = (row < NP ? out + OUT_VP + (size_t)row * 512 : out + OUT_VS + (size_t)(row - NP) * 512) + col0 + bj * HALF; __builtin_nontemporal_store(v0, (GASP f32x4*)of); __builtin_nontemporal_store(v1, (GASP f32x4*)(of + 4)); }
.LBB0_529:
	v_cndmask_b32_e64 v141, v153, v155, s[26:27]
	v_cndmask_b32_e64 v140, v152, v154, s[26:27]
	v_mov_b32_e32 v63, v189
	v_lshl_add_u64 v[140:141], v[140:141], 0, v[62:63]
	v_mbcnt_lo_u32_b32 v238, -1, 0
	v_mbcnt_hi_u32_b32 v238, -1, v238
	v_bfe_i32 v238, v238, 4, 1
	v_lshlrev_b32_e32 v238, 4, v238
	v_ashrrev_i32_e32 v239, 31, v238
	v_lshl_add_u64 v[236:237], v[140:141], 0, v[238:239]
	v_permlane16_swap_b32_e32 v136, v132
	v_permlane16_swap_b32_e32 v137, v133
	v_permlane16_swap_b32_e32 v138, v134
	v_permlane16_swap_b32_e32 v139, v135
	global_store_dwordx4 v[236:237], v[136:139], off nt
	global_store_dwordx4 v[236:237], v[132:135], off offset:32 nt
	s_nop 1
	v_permlane16_swap_b32_e32 v136, v132
	v_permlane16_swap_b32_e32 v137, v133
	v_permlane16_swap_b32_e32 v138, v134
	v_permlane16_swap_b32_e32 v139, v135
	s_and_b64 vcc, exec, s[18:19]
	s_cbranch_vccz .LBB0_525

; #define GASP __attribute__((address_space(1)))
; template <bool PERM>
; __device__ __forceinline__ void ln_fold_fix(Acc& acc, const Unit& u, int wr, int wc, int fr, int fq, const float* c1, const float* c2, LAS unsigned char* lds) {
;     ...
;         for (int n = 0; n < 2; ++n) { const int c = u.pn * BM + bj * HALF + wc * 32 + (PERM ? 8 * fq + 4 * n : 16 * n + 4 * fq);
;             const f32x4 a1 = *(const GASP f32x4*)(c1 + c), a2 = *(const GASP f32x4*)(c2 + c);
; #pragma unroll
;             for (int ai = 0; ai < 2; ++ai)
; #pragma unroll
;                 for (int m = 0; m < 4; ++m) { const f32x2 st = SL[ai * HALF + wr * 64 + m * 16 + fr]; acc[ai][bj][m][n] = (acc[ai][bj][m][n] - a1 * st[0]) * st[1] + a2; } }
;     __device__ __forceinline__ void operator()(Acc& acc, const Unit& u, int wr, int wc, int fr, int fq, LAS unsigned char* lds) const {
;     ...
;                     f32x4 v0 = acc[ai][bj][m][0], v1 = acc[ai][bj][m][1];
;                     const size_t o = (size_t)row * 512 + col0 + bj * HALF;
;                     if (sec == 0) { v0 = v0 * qscale; v1 = v1 * qscale; }
;                     if (sec == 1) { float* of = (row < NP ? out + OUT_KP + (size_t)row * 512 : out + OUT_KS + (size_t)(row - NP) * 512) + col0 + bj * HALF; __builtin_nontemporal_store(v0, (GASP f32x4*)of); __builtin_nontemporal_store(v1, (GASP f32x4*)(of + 4)); }
;                     if (sec == 2) { float* of = (row < NP ? out + OUT_VP + (size_t)row * 512 : out + OUT_VS + (size_t)(row - NP) * 512) + col0 + bj * HALF; __builtin_nontemporal_store(v0, (GASP f32x4*)of); __builtin_nontemporal_store(v1, (GASP f32x4*)(of + 4)); }
.LBB0_545:
	v_xor_b32_e32 v138, 0x80000000, v124
	v_mov_b32_e32 v132, v124
	v_mov_b32_e32 v133, v124
	v_mov_b32_e32 v139, v138
	v_mov_b32_e32 v134, v125
	v_mov_b32_e32 v135, v125
	v_pk_fma_f32 v[128:129], v[132:133], v[36:37], v[128:129] neg_lo:[1,0,0] neg_hi:[1,0,0]
	v_pk_fma_f32 v[130:131], v[138:139], v[38:39], v[130:131]
	v_mov_b32_e32 v124, v125
	v_pk_fma_f32 v[120:121], v[132:133], v[40:41], v[120:121] neg_lo:[1,0,0] neg_hi:[1,0,0]
	v_pk_fma_f32 v[122:123], v[138:139], v[42:43], v[122:123]
	v_pk_fma_f32 v[130:131], v[124:125], v[130:131], v[34:35]
	v_pk_fma_f32 v[128:129], v[134:135], v[128:129], v[32:33]
	v_pk_fma_f32 v[122:123], v[124:125], v[122:123], v[30:31]
	v_pk_fma_f32 v[120:121], v[134:135], v[120:121], v[28:29]
	v_pk_mul_f32 v[124:125], v[130:131], s[78:79] op_sel_hi:[1,0]
	v_pk_mul_f32 v[132:133], v[128:129], s[78:79] op_sel_hi:[1,0]
	v_pk_mul_f32 v[134:135], v[122:123], s[78:79] op_sel_hi:[1,0]
	v_pk_mul_f32 v[138:139], v[120:121], s[78:79] op_sel_hi:[1,0]
	v_cndmask_b32_e64 v129, v129, v133, s[12:13]
	v_cndmask_b32_e64 v128, v128, v132, s[12:13]
	v_cndmask_b32_e64 v131, v131, v125, s[12:13]
	v_cndmask_b32_e64 v130, v130, v124, s[12:13]
	v_cndmask_b32_e64 v121, v121, v139, s[12:13]
	v_cndmask_b32_e64 v120, v120, v138, s[12:13]
	v_cndmask_b32_e64 v123, v123, v135, s[12:13]
	s_and_b64 vcc, exec, s[14:15]
	v_cndmask_b32_e64 v122, v122, v134, s[12:13]
	s_cbranch_vccnz .LBB0_551
	v_cndmask_b32_e64 v125, v149, v151, s[26:27]
	v_cndmask_b32_e64 v124, v148, v150, s[26:27]
	v_mov_b32_e32 v63, v189
	v_lshl_add_u64 v[124:125], v[124:125], 0, v[62:63]
	v_mbcnt_lo_u32_b32 v238, -1, 0
	v_mbcnt_hi_u32_b32 v238, -1, v238
	v_bfe_i32 v238, v238, 4, 1
	v_lshlrev_b32_e32 v238, 4, v238
	v_ashrrev_i32_e32 v239, 31, v238
	v_lshl_add_u64 v[236:237], v[124:125], 0, v[238:239]
	v_permlane16_swap_b32_e32 v128, v120
	v_permlane16_swap_b32_e32 v129, v121
	v_permlane16_swap_b32_e32 v130, v122
	v_permlane16_swap_b32_e32 v131, v123
	global_store_dwordx4 v[236:237], v[128:131], off offset:512 nt
	global_store_dwordx4 v[236:237], v[120:123], off offset:544 nt
	s_nop 1
	v_permlane16_swap_b32_e32 v128, v120
	v_permlane16_swap_b32_e32 v129, v121
	v_permlane16_swap_b32_e32 v130, v122
	v_permlane16_swap_b32_e32 v131, v123
	s_and_b64 vcc, exec, s[16:17]
	s_cbranch_vccz .LBB0_552

; #define GASP __attribute__((address_space(1)))
;     __device__ __forceinline__ void operator()(Acc& acc, const Unit& u, int wr, int wc, int fr, int fq, LAS unsigned char* lds) const {
;     ...
;                     f32x4 v0 = acc[ai][bj][m][0], v1 = acc[ai][bj][m][1];
;                     const size_t o = (size_t)row * 512 + col0 + bj * HALF;
;                     if (sec == 0) { v0 = v0 * qscale; v1 = v1 * qscale; }
;                     if (sec == 1) { float* of = (row < NP ? out + OUT_KP + (size_t)row * 512 : out + OUT_KS + (size_t)(row - NP) * 512) + col0 + bj * HALF; __builtin_nontemporal_store(v0, (GASP f32x4*)of); __builtin_nontemporal_store(v1, (GASP f32x4*)(of + 4)); }
;                     if (sec == 2) { float* of = (row < NP ? out + OUT_VP + (size_t)row * 512 : out + OUT_VS + (size_t)(row - NP) * 512) + col0 + bj * HALF; __builtin_nontemporal_store(v0, (GASP f32x4*)of); __builtin_nontemporal_store(v1, (GASP f32x4*)(of + 4)); }
.LBB0_552:
	v_cndmask_b32_e64 v125, v153, v155, s[26:27]
	v_cndmask_b32_e64 v124, v152, v154, s[26:27]
	v_mov_b32_e32 v63, v189
	v_lshl_add_u64 v[124:125], v[124:125], 0, v[62:63]
	v_mbcnt_lo_u32_b32 v238, -1, 0
	v_mbcnt_hi_u32_b32 v238, -1, v238
	v_bfe_i32 v238, v238, 4, 1
	v_lshlrev_b32_e32 v238, 4, v238
	v_ashrrev_i32_e32 v239, 31, v238
	v_lshl_add_u64 v[236:237], v[124:125], 0, v[238:239]
	v_permlane16_swap_b32_e32 v128, v120
	v_permlane16_swap_b32_e32 v129, v121
	v_permlane16_swap_b32_e32 v130, v122
	v_permlane16_swap_b32_e32 v131, v123
	global_store_dwordx4 v[236:237], v[128:131], off offset:512 nt
	global_store_dwordx4 v[236:237], v[120:123], off offset:544 nt
	s_nop 1
	v_permlane16_swap_b32_e32 v128, v120
	v_permlane16_swap_b32_e32 v129, v121
	v_permlane16_swap_b32_e32 v130, v122
	v_permlane16_swap_b32_e32 v131, v123
	s_and_b64 vcc, exec, s[18:19]
	s_cbranch_vccz .LBB0_548

; #define GASP __attribute__((address_space(1)))
; template <bool PERM>
; __device__ __forceinline__ void ln_fold_fix(Acc& acc, const Unit& u, int wr, int wc, int fr, int fq, const float* c1, const float* c2, LAS unsigned char* lds) {
;     ...
;         for (int n = 0; n < 2; ++n) { const int c = u.pn * BM + bj * HALF + wc * 32 + (PERM ? 8 * fq + 4 * n : 16 * n + 4 * fq);
;             const f32x4 a1 = *(const GASP f32x4*)(c1 + c), a2 = *(const GASP f32x4*)(c2 + c);
; #pragma unroll
;             for (int ai = 0; ai < 2; ++ai)
; #pragma unroll
;                 for (int m = 0; m < 4; ++m) { const f32x2 st = SL[ai * HALF + wr * 64 + m * 16 + fr]; acc[ai][bj][m][n] = (acc[ai][bj][m][n] - a1 * st[0]) * st[1] + a2; } }
;     __device__ __forceinline__ void operator()(Acc& acc, const Unit& u, int wr, int wc, int fr, int fq, LAS unsigned char* lds) const {
;     ...
;                     f32x4 v0 = acc[ai][bj][m][0], v1 = acc[ai][bj][m][1];
;                     const size_t o = (size_t)row * 512 + col0 + bj * HALF;
;                     if (sec == 0) { v0 = v0 * qscale; v1 = v1 * qscale; }
;                     if (sec == 1) { float* of = (row < NP ? out + OUT_KP + (size_t)row * 512 : out + OUT_KS + (size_t)(row - NP) * 512) + col0 + bj * HALF; __builtin_nontemporal_store(v0, (GASP f32x4*)of); __builtin_nontemporal_store(v1, (GASP f32x4*)(of + 4)); }
;                     if (sec == 2) { float* of = (row < NP ? out + OUT_VP + (size_t)row * 512 : out + OUT_VS + (size_t)(row - NP) * 512) + col0 + bj * HALF; __builtin_nontemporal_store(v0, (GASP f32x4*)of); __builtin_nontemporal_store(v1, (GASP f32x4*)(of + 4)); }
.LBB0_571:
	v_pk_fma_f32 v[116:117], v[60:61], v[126:127], v[116:117] op_sel_hi:[1,0,1] neg_lo:[1,0,0] neg_hi:[1,0,0]
	v_pk_fma_f32 v[118:119], v[198:199], v[126:127], v[118:119] op_sel_hi:[1,0,1]
	v_pk_fma_f32 v[112:113], v[126:127], v[52:53], v[112:113] op_sel_hi:[0,1,1] neg_lo:[1,0,0] neg_hi:[1,0,0]
	v_pk_fma_f32 v[114:115], v[126:127], v[54:55], v[114:115] op_sel_hi:[0,1,1] neg_lo:[1,0,0] neg_hi:[1,0,0]
	v_or_b32_e32 v124, 48, v200
	v_pk_fma_f32 v[118:119], v[126:127], v[118:119], v[66:67] op_sel:[1,0,0]
	v_pk_fma_f32 v[116:117], v[126:127], v[116:117], v[64:65] op_sel:[1,0,0]
	v_pk_fma_f32 v[114:115], v[126:127], v[114:115], v[58:59] op_sel:[1,0,0]
	v_pk_fma_f32 v[112:113], v[126:127], v[112:113], v[56:57] op_sel:[1,0,0]
	v_ashrrev_i32_e32 v125, 31, v124
	v_add_u32_e32 v188, 0xffff8030, v200
	v_lshlrev_b64 v[128:129], 9, v[124:125]
	v_lshlrev_b64 v[120:121], 11, v[188:189]
	s_waitcnt lgkmcnt(0)
	v_pk_mul_f32 v[122:123], v[118:119], s[78:79] op_sel_hi:[1,0]
	v_pk_mul_f32 v[130:131], v[116:117], s[78:79] op_sel_hi:[1,0]
	v_pk_mul_f32 v[132:133], v[114:115], s[78:79] op_sel_hi:[1,0]
	v_pk_mul_f32 v[134:135], v[112:113], s[78:79] op_sel_hi:[1,0]
	v_cmp_gt_i32_e64 s[26:27], s51, v124
	v_cndmask_b32_e64 v117, v117, v131, s[12:13]
	v_cndmask_b32_e64 v116, v116, v130, s[12:13]
	v_cndmask_b32_e64 v119, v119, v123, s[12:13]
	v_cndmask_b32_e64 v118, v118, v122, s[12:13]
	v_cndmask_b32_e64 v113, v113, v135, s[12:13]
	v_cndmask_b32_e64 v112, v112, v134, s[12:13]
	v_cndmask_b32_e64 v115, v115, v133, s[12:13]
	v_cndmask_b32_e64 v114, v114, v132, s[12:13]
	s_and_b64 vcc, exec, s[14:15]
	v_lshl_add_u64 v[130:131], s[72:73], 0, v[120:121]
	v_lshl_add_u64 v[132:133], v[128:129], 2, s[70:71]
	s_cbranch_vccnz .LBB0_577
	v_cndmask_b32_e64 v123, v131, v133, s[26:27]
	v_cndmask_b32_e64 v122, v130, v132, s[26:27]
	v_mov_b32_e32 v63, v189
	v_lshl_add_u64 v[122:123], v[122:123], 0, v[62:63]
	v_mbcnt_lo_u32_b32 v238, -1, 0
	v_mbcnt_hi_u32_b32 v238, -1, v238
	v_bfe_i32 v238, v238, 4, 1
	v_lshlrev_b32_e32 v238, 4, v238
	v_ashrrev_i32_e32 v239, 31, v238
	v_lshl_add_u64 v[236:237], v[122:123], 0, v[238:239]
	v_permlane16_swap_b32_e32 v116, v112
	v_permlane16_swap_b32_e32 v117, v113
	v_permlane16_swap_b32_e32 v118, v114
	v_permlane16_swap_b32_e32 v119, v115
	global_store_dwordx4 v[236:237], v[116:119], off nt
	global_store_dwordx4 v[236:237], v[112:115], off offset:32 nt
	s_nop 1
	v_permlane16_swap_b32_e32 v116, v112
	v_permlane16_swap_b32_e32 v117, v113
	v_permlane16_swap_b32_e32 v118, v114
	v_permlane16_swap_b32_e32 v119, v115
	s_and_b64 vcc, exec, s[16:17]
	v_lshl_add_u64 v[134:135], s[76:77], 0, v[120:121]
	v_lshl_add_u64 v[136:137], v[128:129], 2, s[74:75]
	s_cbranch_vccz .LBB0_578

; #define GASP __attribute__((address_space(1)))
;     __device__ __forceinline__ void operator()(Acc& acc, const Unit& u, int wr, int wc, int fr, int fq, LAS unsigned char* lds) const {
;     ...
;                     f32x4 v0 = acc[ai][bj][m][0], v1 = acc[ai][bj][m][1];
;                     const size_t o = (size_t)row * 512 + col0 + bj * HALF;
;                     if (sec == 0) { v0 = v0 * qscale; v1 = v1 * qscale; }
;                     if (sec == 1) { float* of = (row < NP ? out + OUT_KP + (size_t)row * 512 : out + OUT_KS + (size_t)(row - NP) * 512) + col0 + bj * HALF; __builtin_nontemporal_store(v0, (GASP f32x4*)of); __builtin_nontemporal_store(v1, (GASP f32x4*)(of + 4)); }
;                     if (sec == 2) { float* of = (row < NP ? out + OUT_VP + (size_t)row * 512 : out + OUT_VS + (size_t)(row - NP) * 512) + col0 + bj * HALF; __builtin_nontemporal_store(v0, (GASP f32x4*)of); __builtin_nontemporal_store(v1, (GASP f32x4*)(of + 4)); }
.LBB0_578:
	v_cndmask_b32_e64 v121, v135, v137, s[26:27]
	v_cndmask_b32_e64 v120, v134, v136, s[26:27]
	v_mov_b32_e32 v63, v189
	v_lshl_add_u64 v[120:121], v[120:121], 0, v[62:63]
	v_mbcnt_lo_u32_b32 v238, -1, 0
	v_mbcnt_hi_u32_b32 v238, -1, v238
	v_bfe_i32 v238, v238, 4, 1
	v_lshlrev_b32_e32 v238, 4, v238
	v_ashrrev_i32_e32 v239, 31, v238
	v_lshl_add_u64 v[236:237], v[120:121], 0, v[238:239]
	v_permlane16_swap_b32_e32 v116, v112
	v_permlane16_swap_b32_e32 v117, v113
	v_permlane16_swap_b32_e32 v118, v114
	v_permlane16_swap_b32_e32 v119, v115
	global_store_dwordx4 v[236:237], v[116:119], off nt
	global_store_dwordx4 v[236:237], v[112:115], off offset:32 nt
	s_nop 1
	v_permlane16_swap_b32_e32 v116, v112
	v_permlane16_swap_b32_e32 v117, v113
	v_permlane16_swap_b32_e32 v118, v114
	v_permlane16_swap_b32_e32 v119, v115
	s_and_b64 vcc, exec, s[18:19]
	s_cbranch_vccz .LBB0_574

; #define GASP __attribute__((address_space(1)))
; template <bool PERM>
; __device__ __forceinline__ void ln_fold_fix(Acc& acc, const Unit& u, int wr, int wc, int fr, int fq, const float* c1, const float* c2, LAS unsigned char* lds) {
;     ...
;         for (int n = 0; n < 2; ++n) { const int c = u.pn * BM + bj * HALF + wc * 32 + (PERM ? 8 * fq + 4 * n : 16 * n + 4 * fq);
;             const f32x4 a1 = *(const GASP f32x4*)(c1 + c), a2 = *(const GASP f32x4*)(c2 + c);
; #pragma unroll
;             for (int ai = 0; ai < 2; ++ai)
; #pragma unroll
;                 for (int m = 0; m < 4; ++m) { const f32x2 st = SL[ai * HALF + wr * 64 + m * 16 + fr]; acc[ai][bj][m][n] = (acc[ai][bj][m][n] - a1 * st[0]) * st[1] + a2; } }
;     __device__ __forceinline__ void operator()(Acc& acc, const Unit& u, int wr, int wc, int fr, int fq, LAS unsigned char* lds) const {
;     ...
;                     f32x4 v0 = acc[ai][bj][m][0], v1 = acc[ai][bj][m][1];
;                     const size_t o = (size_t)row * 512 + col0 + bj * HALF;
;                     if (sec == 0) { v0 = v0 * qscale; v1 = v1 * qscale; }
;                     if (sec == 1) { float* of = (row < NP ? out + OUT_KP + (size_t)row * 512 : out + OUT_KS + (size_t)(row - NP) * 512) + col0 + bj * HALF; __builtin_nontemporal_store(v0, (GASP f32x4*)of); __builtin_nontemporal_store(v1, (GASP f32x4*)(of + 4)); }
;                     if (sec == 2) { float* of = (row < NP ? out + OUT_VP + (size_t)row * 512 : out + OUT_VS + (size_t)(row - NP) * 512) + col0 + bj * HALF; __builtin_nontemporal_store(v0, (GASP f32x4*)of); __builtin_nontemporal_store(v1, (GASP f32x4*)(of + 4)); }
.LBB0_594:
	v_xor_b32_e32 v118, 0x80000000, v126
	v_mov_b32_e32 v112, v126
	v_mov_b32_e32 v113, v126
	v_mov_b32_e32 v119, v118
	v_mov_b32_e32 v114, v127
	v_mov_b32_e32 v115, v127
	v_pk_fma_f32 v[108:109], v[112:113], v[36:37], v[108:109] neg_lo:[1,0,0] neg_hi:[1,0,0]
	v_pk_fma_f32 v[110:111], v[118:119], v[38:39], v[110:111]
	v_mov_b32_e32 v126, v127
	v_pk_fma_f32 v[104:105], v[112:113], v[40:41], v[104:105] neg_lo:[1,0,0] neg_hi:[1,0,0]
	v_pk_fma_f32 v[106:107], v[118:119], v[42:43], v[106:107]
	v_pk_fma_f32 v[110:111], v[126:127], v[110:111], v[34:35]
	v_pk_fma_f32 v[108:109], v[114:115], v[108:109], v[32:33]
	v_pk_fma_f32 v[106:107], v[126:127], v[106:107], v[30:31]
	v_pk_fma_f32 v[104:105], v[114:115], v[104:105], v[28:29]
	v_pk_mul_f32 v[112:113], v[110:111], s[78:79] op_sel_hi:[1,0]
	v_pk_mul_f32 v[114:115], v[108:109], s[78:79] op_sel_hi:[1,0]
	v_pk_mul_f32 v[118:119], v[106:107], s[78:79] op_sel_hi:[1,0]
	v_pk_mul_f32 v[120:121], v[104:105], s[78:79] op_sel_hi:[1,0]
	v_cndmask_b32_e64 v109, v109, v115, s[12:13]
	v_cndmask_b32_e64 v108, v108, v114, s[12:13]
	v_cndmask_b32_e64 v111, v111, v113, s[12:13]
	v_cndmask_b32_e64 v110, v110, v112, s[12:13]
	v_cndmask_b32_e64 v105, v105, v121, s[12:13]
	v_cndmask_b32_e64 v104, v104, v120, s[12:13]
	v_cndmask_b32_e64 v107, v107, v119, s[12:13]
	s_and_b64 vcc, exec, s[14:15]
	v_cndmask_b32_e64 v106, v106, v118, s[12:13]
	s_cbranch_vccnz .LBB0_600
	v_cndmask_b32_e64 v113, v131, v133, s[26:27]
	v_cndmask_b32_e64 v112, v130, v132, s[26:27]
	v_mov_b32_e32 v63, v189
	v_lshl_add_u64 v[112:113], v[112:113], 0, v[62:63]
	v_mbcnt_lo_u32_b32 v238, -1, 0
	v_mbcnt_hi_u32_b32 v238, -1, v238
	v_bfe_i32 v238, v238, 4, 1
	v_lshlrev_b32_e32 v238, 4, v238
	v_ashrrev_i32_e32 v239, 31, v238
	v_lshl_add_u64 v[236:237], v[112:113], 0, v[238:239]
	v_permlane16_swap_b32_e32 v108, v104
	v_permlane16_swap_b32_e32 v109, v105
	v_permlane16_swap_b32_e32 v110, v106
	v_permlane16_swap_b32_e32 v111, v107
	global_store_dwordx4 v[236:237], v[108:111], off offset:512 nt
	global_store_dwordx4 v[236:237], v[104:107], off offset:544 nt
	s_nop 1
	v_permlane16_swap_b32_e32 v108, v104
	v_permlane16_swap_b32_e32 v109, v105
	v_permlane16_swap_b32_e32 v110, v106
	v_permlane16_swap_b32_e32 v111, v107
	s_and_b64 vcc, exec, s[16:17]
	s_cbranch_vccz .LBB0_601

; #define GASP __attribute__((address_space(1)))
;     __device__ __forceinline__ void operator()(Acc& acc, const Unit& u, int wr, int wc, int fr, int fq, LAS unsigned char* lds) const {
;     ...
;                     f32x4 v0 = acc[ai][bj][m][0], v1 = acc[ai][bj][m][1];
;                     const size_t o = (size_t)row * 512 + col0 + bj * HALF;
;                     if (sec == 0) { v0 = v0 * qscale; v1 = v1 * qscale; }
;                     if (sec == 1) { float* of = (row < NP ? out + OUT_KP + (size_t)row * 512 : out + OUT_KS + (size_t)(row - NP) * 512) + col0 + bj * HALF; __builtin_nontemporal_store(v0, (GASP f32x4*)of); __builtin_nontemporal_store(v1, (GASP f32x4*)(of + 4)); }
;                     if (sec == 2) { float* of = (row < NP ? out + OUT_VP + (size_t)row * 512 : out + OUT_VS + (size_t)(row - NP) * 512) + col0 + bj * HALF; __builtin_nontemporal_store(v0, (GASP f32x4*)of); __builtin_nontemporal_store(v1, (GASP f32x4*)(of + 4)); }
.LBB0_601:
	v_cndmask_b32_e64 v113, v135, v137, s[26:27]
	v_cndmask_b32_e64 v112, v134, v136, s[26:27]
	v_mov_b32_e32 v63, v189
	v_lshl_add_u64 v[112:113], v[112:113], 0, v[62:63]
	v_mbcnt_lo_u32_b32 v238, -1, 0
	v_mbcnt_hi_u32_b32 v238, -1, v238
	v_bfe_i32 v238, v238, 4, 1
	v_lshlrev_b32_e32 v238, 4, v238
	v_ashrrev_i32_e32 v239, 31, v238
	v_lshl_add_u64 v[236:237], v[112:113], 0, v[238:239]
	v_permlane16_swap_b32_e32 v108, v104
	v_permlane16_swap_b32_e32 v109, v105
	v_permlane16_swap_b32_e32 v110, v106
	v_permlane16_swap_b32_e32 v111, v107
	global_store_dwordx4 v[236:237], v[108:111], off offset:512 nt
	global_store_dwordx4 v[236:237], v[104:107], off offset:544 nt
	s_nop 1
	v_permlane16_swap_b32_e32 v108, v104
	v_permlane16_swap_b32_e32 v109, v105
	v_permlane16_swap_b32_e32 v110, v106
	v_permlane16_swap_b32_e32 v111, v107
	s_and_b64 vcc, exec, s[18:19]
	s_cbranch_vccz .LBB0_597

; #define GASP __attribute__((address_space(1)))
; template <bool PERM>
; __device__ __forceinline__ void ln_fold_fix(Acc& acc, const Unit& u, int wr, int wc, int fr, int fq, const float* c1, const float* c2, LAS unsigned char* lds) {
;     ...
;         for (int n = 0; n < 2; ++n) { const int c = u.pn * BM + bj * HALF + wc * 32 + (PERM ? 8 * fq + 4 * n : 16 * n + 4 * fq);
;             const f32x4 a1 = *(const GASP f32x4*)(c1 + c), a2 = *(const GASP f32x4*)(c2 + c);
; #pragma unroll
;             for (int ai = 0; ai < 2; ++ai)
; #pragma unroll
;                 for (int m = 0; m < 4; ++m) { const f32x2 st = SL[ai * HALF + wr * 64 + m * 16 + fr]; acc[ai][bj][m][n] = (acc[ai][bj][m][n] - a1 * st[0]) * st[1] + a2; } }
;     __device__ __forceinline__ void operator()(Acc& acc, const Unit& u, int wr, int wc, int fr, int fq, LAS unsigned char* lds) const {
;     ...
;                     f32x4 v0 = acc[ai][bj][m][0], v1 = acc[ai][bj][m][1];
;                     const size_t o = (size_t)row * 512 + col0 + bj * HALF;
;                     if (sec == 0) { v0 = v0 * qscale; v1 = v1 * qscale; }
;                     if (sec == 1) { float* of = (row < NP ? out + OUT_KP + (size_t)row * 512 : out + OUT_KS + (size_t)(row - NP) * 512) + col0 + bj * HALF; __builtin_nontemporal_store(v0, (GASP f32x4*)of); __builtin_nontemporal_store(v1, (GASP f32x4*)(of + 4)); }
;                     if (sec == 2) { float* of = (row < NP ? out + OUT_VP + (size_t)row * 512 : out + OUT_VS + (size_t)(row - NP) * 512) + col0 + bj * HALF; __builtin_nontemporal_store(v0, (GASP f32x4*)of); __builtin_nontemporal_store(v1, (GASP f32x4*)(of + 4)); }
.LBB0_620:
	v_pk_fma_f32 v[100:101], v[60:61], v[92:93], v[100:101] op_sel_hi:[1,0,1] neg_lo:[1,0,0] neg_hi:[1,0,0]
	v_pk_fma_f32 v[102:103], v[198:199], v[92:93], v[102:103] op_sel_hi:[1,0,1]
	v_pk_fma_f32 v[96:97], v[92:93], v[52:53], v[96:97] op_sel_hi:[0,1,1] neg_lo:[1,0,0] neg_hi:[1,0,0]
	v_pk_fma_f32 v[98:99], v[92:93], v[54:55], v[98:99] op_sel_hi:[0,1,1] neg_lo:[1,0,0] neg_hi:[1,0,0]
	v_add_u32_e32 v108, 0x80, v200
	v_pk_fma_f32 v[102:103], v[92:93], v[102:103], v[66:67] op_sel:[1,0,0]
	v_pk_fma_f32 v[100:101], v[92:93], v[100:101], v[64:65] op_sel:[1,0,0]
	v_pk_fma_f32 v[98:99], v[92:93], v[98:99], v[58:59] op_sel:[1,0,0]
	v_pk_fma_f32 v[96:97], v[92:93], v[96:97], v[56:57] op_sel:[1,0,0]
	v_ashrrev_i32_e32 v109, 31, v108
	v_add_u32_e32 v188, 0xffff8080, v200
	v_lshlrev_b64 v[110:111], 9, v[108:109]
	s_movk_i32 s26, 0x7f80
	v_lshlrev_b64 v[104:105], 11, v[188:189]
	s_waitcnt lgkmcnt(0)
	v_pk_mul_f32 v[106:107], v[102:103], s[78:79] op_sel_hi:[1,0]
	v_pk_mul_f32 v[112:113], v[100:101], s[78:79] op_sel_hi:[1,0]
	v_pk_mul_f32 v[114:115], v[98:99], s[78:79] op_sel_hi:[1,0]
	v_pk_mul_f32 v[116:117], v[96:97], s[78:79] op_sel_hi:[1,0]
	v_cmp_gt_i32_e64 s[26:27], s26, v200
	v_cndmask_b32_e64 v101, v101, v113, s[12:13]
	v_cndmask_b32_e64 v100, v100, v112, s[12:13]
	v_cndmask_b32_e64 v103, v103, v107, s[12:13]
	v_cndmask_b32_e64 v102, v102, v106, s[12:13]
	v_cndmask_b32_e64 v97, v97, v117, s[12:13]
	v_cndmask_b32_e64 v96, v96, v116, s[12:13]
	v_cndmask_b32_e64 v99, v99, v115, s[12:13]
	v_cndmask_b32_e64 v98, v98, v114, s[12:13]
	s_and_b64 vcc, exec, s[14:15]
	v_lshl_add_u64 v[112:113], s[72:73], 0, v[104:105]
	v_lshl_add_u64 v[114:115], v[110:111], 2, s[70:71]
	s_cbranch_vccnz .LBB0_626
	v_cndmask_b32_e64 v107, v113, v115, s[26:27]
	v_cndmask_b32_e64 v106, v112, v114, s[26:27]
	v_mov_b32_e32 v63, v189
	v_lshl_add_u64 v[106:107], v[106:107], 0, v[62:63]
	v_mbcnt_lo_u32_b32 v238, -1, 0
	v_mbcnt_hi_u32_b32 v238, -1, v238
	v_bfe_i32 v238, v238, 4, 1
	v_lshlrev_b32_e32 v238, 4, v238
	v_ashrrev_i32_e32 v239, 31, v238
	v_lshl_add_u64 v[236:237], v[106:107], 0, v[238:239]
	v_permlane16_swap_b32_e32 v100, v96
	v_permlane16_swap_b32_e32 v101, v97
	v_permlane16_swap_b32_e32 v102, v98
	v_permlane16_swap_b32_e32 v103, v99
	global_store_dwordx4 v[236:237], v[100:103], off nt
	global_store_dwordx4 v[236:237], v[96:99], off offset:32 nt
	s_nop 1
	v_permlane16_swap_b32_e32 v100, v96
	v_permlane16_swap_b32_e32 v101, v97
	v_permlane16_swap_b32_e32 v102, v98
	v_permlane16_swap_b32_e32 v103, v99
	s_and_b64 vcc, exec, s[16:17]
	v_lshl_add_u64 v[116:117], s[76:77], 0, v[104:105]
	v_lshl_add_u64 v[118:119], v[110:111], 2, s[74:75]
	s_cbranch_vccz .LBB0_627

; #define GASP __attribute__((address_space(1)))
;     __device__ __forceinline__ void operator()(Acc& acc, const Unit& u, int wr, int wc, int fr, int fq, LAS unsigned char* lds) const {
;     ...
;                     f32x4 v0 = acc[ai][bj][m][0], v1 = acc[ai][bj][m][1];
;                     const size_t o = (size_t)row * 512 + col0 + bj * HALF;
;                     if (sec == 0) { v0 = v0 * qscale; v1 = v1 * qscale; }
;                     if (sec == 1) { float* of = (row < NP ? out + OUT_KP + (size_t)row * 512 : out + OUT_KS + (size_t)(row - NP) * 512) + col0 + bj * HALF; __builtin_nontemporal_store(v0, (GASP f32x4*)of); __builtin_nontemporal_store(v1, (GASP f32x4*)(of + 4)); }
;                     if (sec == 2) { float* of = (row < NP ? out + OUT_VP + (size_t)row * 512 : out + OUT_VS + (size_t)(row - NP) * 512) + col0 + bj * HALF; __builtin_nontemporal_store(v0, (GASP f32x4*)of); __builtin_nontemporal_store(v1, (GASP f32x4*)(of + 4)); }
.LBB0_627:
	v_cndmask_b32_e64 v105, v117, v119, s[26:27]
	v_cndmask_b32_e64 v104, v116, v118, s[26:27]
	v_mov_b32_e32 v63, v189
	v_lshl_add_u64 v[104:105], v[104:105], 0, v[62:63]
	v_mbcnt_lo_u32_b32 v238, -1, 0
	v_mbcnt_hi_u32_b32 v238, -1, v238
	v_bfe_i32 v238, v238, 4, 1
	v_lshlrev_b32_e32 v238, 4, v238
	v_ashrrev_i32_e32 v239, 31, v238
	v_lshl_add_u64 v[236:237], v[104:105], 0, v[238:239]
	v_permlane16_swap_b32_e32 v100, v96
	v_permlane16_swap_b32_e32 v101, v97
	v_permlane16_swap_b32_e32 v102, v98
	v_permlane16_swap_b32_e32 v103, v99
	global_store_dwordx4 v[236:237], v[100:103], off nt
	global_store_dwordx4 v[236:237], v[96:99], off offset:32 nt
	s_nop 1
	v_permlane16_swap_b32_e32 v100, v96
	v_permlane16_swap_b32_e32 v101, v97
	v_permlane16_swap_b32_e32 v102, v98
	v_permlane16_swap_b32_e32 v103, v99
	s_and_b64 vcc, exec, s[18:19]
	s_cbranch_vccz .LBB0_623

; #define GASP __attribute__((address_space(1)))
; template <bool PERM>
; __device__ __forceinline__ void ln_fold_fix(Acc& acc, const Unit& u, int wr, int wc, int fr, int fq, const float* c1, const float* c2, LAS unsigned char* lds) {
;     ...
;         for (int n = 0; n < 2; ++n) { const int c = u.pn * BM + bj * HALF + wc * 32 + (PERM ? 8 * fq + 4 * n : 16 * n + 4 * fq);
;             const f32x4 a1 = *(const GASP f32x4*)(c1 + c), a2 = *(const GASP f32x4*)(c2 + c);
; #pragma unroll
;             for (int ai = 0; ai < 2; ++ai)
; #pragma unroll
;                 for (int m = 0; m < 4; ++m) { const f32x2 st = SL[ai * HALF + wr * 64 + m * 16 + fr]; acc[ai][bj][m][n] = (acc[ai][bj][m][n] - a1 * st[0]) * st[1] + a2; } }
;     __device__ __forceinline__ void operator()(Acc& acc, const Unit& u, int wr, int wc, int fr, int fq, LAS unsigned char* lds) const {
;     ...
;                     f32x4 v0 = acc[ai][bj][m][0], v1 = acc[ai][bj][m][1];
;                     const size_t o = (size_t)row * 512 + col0 + bj * HALF;
;                     if (sec == 0) { v0 = v0 * qscale; v1 = v1 * qscale; }
;                     if (sec == 1) { float* of = (row < NP ? out + OUT_KP + (size_t)row * 512 : out + OUT_KS + (size_t)(row - NP) * 512) + col0 + bj * HALF; __builtin_nontemporal_store(v0, (GASP f32x4*)of); __builtin_nontemporal_store(v1, (GASP f32x4*)(of + 4)); }
;                     if (sec == 2) { float* of = (row < NP ? out + OUT_VP + (size_t)row * 512 : out + OUT_VS + (size_t)(row - NP) * 512) + col0 + bj * HALF; __builtin_nontemporal_store(v0, (GASP f32x4*)of); __builtin_nontemporal_store(v1, (GASP f32x4*)(of + 4)); }
.LBB0_643:
	v_xor_b32_e32 v102, 0x80000000, v92
	v_mov_b32_e32 v96, v92
	v_mov_b32_e32 v97, v92
	v_mov_b32_e32 v103, v102
	v_mov_b32_e32 v98, v93
	v_mov_b32_e32 v99, v93
	v_pk_fma_f32 v[88:89], v[96:97], v[36:37], v[88:89] neg_lo:[1,0,0] neg_hi:[1,0,0]
	v_pk_fma_f32 v[90:91], v[102:103], v[38:39], v[90:91]
	v_mov_b32_e32 v92, v93
	v_pk_fma_f32 v[84:85], v[96:97], v[40:41], v[84:85] neg_lo:[1,0,0] neg_hi:[1,0,0]
	v_pk_fma_f32 v[86:87], v[102:103], v[42:43], v[86:87]
	v_pk_fma_f32 v[90:91], v[92:93], v[90:91], v[34:35]
	v_pk_fma_f32 v[88:89], v[98:99], v[88:89], v[32:33]
	v_pk_fma_f32 v[86:87], v[92:93], v[86:87], v[30:31]
	v_pk_fma_f32 v[84:85], v[98:99], v[84:85], v[28:29]
	v_pk_mul_f32 v[92:93], v[90:91], s[78:79] op_sel_hi:[1,0]
	v_pk_mul_f32 v[96:97], v[88:89], s[78:79] op_sel_hi:[1,0]
	v_pk_mul_f32 v[98:99], v[86:87], s[78:79] op_sel_hi:[1,0]
	v_pk_mul_f32 v[102:103], v[84:85], s[78:79] op_sel_hi:[1,0]
	v_cndmask_b32_e64 v89, v89, v97, s[12:13]
	v_cndmask_b32_e64 v88, v88, v96, s[12:13]
	v_cndmask_b32_e64 v91, v91, v93, s[12:13]
	v_cndmask_b32_e64 v90, v90, v92, s[12:13]
	v_cndmask_b32_e64 v85, v85, v103, s[12:13]
	v_cndmask_b32_e64 v84, v84, v102, s[12:13]
	v_cndmask_b32_e64 v87, v87, v99, s[12:13]
	s_and_b64 vcc, exec, s[14:15]
	v_cndmask_b32_e64 v86, v86, v98, s[12:13]
	s_cbranch_vccnz .LBB0_649
	v_cndmask_b32_e64 v93, v113, v115, s[26:27]
	v_cndmask_b32_e64 v92, v112, v114, s[26:27]
	v_mov_b32_e32 v63, v189
	v_lshl_add_u64 v[92:93], v[92:93], 0, v[62:63]
	v_mbcnt_lo_u32_b32 v238, -1, 0
	v_mbcnt_hi_u32_b32 v238, -1, v238
	v_bfe_i32 v238, v238, 4, 1
	v_lshlrev_b32_e32 v238, 4, v238
	v_ashrrev_i32_e32 v239, 31, v238
	v_lshl_add_u64 v[236:237], v[92:93], 0, v[238:239]
	v_permlane16_swap_b32_e32 v88, v84
	v_permlane16_swap_b32_e32 v89, v85
	v_permlane16_swap_b32_e32 v90, v86
	v_permlane16_swap_b32_e32 v91, v87
	global_store_dwordx4 v[236:237], v[88:91], off offset:512 nt
	global_store_dwordx4 v[236:237], v[84:87], off offset:544 nt
	s_nop 1
	v_permlane16_swap_b32_e32 v88, v84
	v_permlane16_swap_b32_e32 v89, v85
	v_permlane16_swap_b32_e32 v90, v86
	v_permlane16_swap_b32_e32 v91, v87
	s_and_b64 vcc, exec, s[16:17]
	s_cbranch_vccz .LBB0_650

; #define GASP __attribute__((address_space(1)))
;     __device__ __forceinline__ void operator()(Acc& acc, const Unit& u, int wr, int wc, int fr, int fq, LAS unsigned char* lds) const {
;     ...
;                     f32x4 v0 = acc[ai][bj][m][0], v1 = acc[ai][bj][m][1];
;                     const size_t o = (size_t)row * 512 + col0 + bj * HALF;
;                     if (sec == 0) { v0 = v0 * qscale; v1 = v1 * qscale; }
;                     if (sec == 1) { float* of = (row < NP ? out + OUT_KP + (size_t)row * 512 : out + OUT_KS + (size_t)(row - NP) * 512) + col0 + bj * HALF; __builtin_nontemporal_store(v0, (GASP f32x4*)of); __builtin_nontemporal_store(v1, (GASP f32x4*)(of + 4)); }
;                     if (sec == 2) { float* of = (row < NP ? out + OUT_VP + (size_t)row * 512 : out + OUT_VS + (size_t)(row - NP) * 512) + col0 + bj * HALF; __builtin_nontemporal_store(v0, (GASP f32x4*)of); __builtin_nontemporal_store(v1, (GASP f32x4*)(of + 4)); }
.LBB0_650:
	v_cndmask_b32_e64 v93, v117, v119, s[26:27]
	v_cndmask_b32_e64 v92, v116, v118, s[26:27]
	v_mov_b32_e32 v63, v189
	v_lshl_add_u64 v[92:93], v[92:93], 0, v[62:63]
	v_mbcnt_lo_u32_b32 v238, -1, 0
	v_mbcnt_hi_u32_b32 v238, -1, v238
	v_bfe_i32 v238, v238, 4, 1
	v_lshlrev_b32_e32 v238, 4, v238
	v_ashrrev_i32_e32 v239, 31, v238
	v_lshl_add_u64 v[236:237], v[92:93], 0, v[238:239]
	v_permlane16_swap_b32_e32 v88, v84
	v_permlane16_swap_b32_e32 v89, v85
	v_permlane16_swap_b32_e32 v90, v86
	v_permlane16_swap_b32_e32 v91, v87
	global_store_dwordx4 v[236:237], v[88:91], off offset:512 nt
	global_store_dwordx4 v[236:237], v[84:87], off offset:544 nt
	s_nop 1
	v_permlane16_swap_b32_e32 v88, v84
	v_permlane16_swap_b32_e32 v89, v85
	v_permlane16_swap_b32_e32 v90, v86
	v_permlane16_swap_b32_e32 v91, v87
	s_and_b64 vcc, exec, s[18:19]
	s_cbranch_vccz .LBB0_646

; #define GASP __attribute__((address_space(1)))
; template <bool PERM>
; __device__ __forceinline__ void ln_fold_fix(Acc& acc, const Unit& u, int wr, int wc, int fr, int fq, const float* c1, const float* c2, LAS unsigned char* lds) {
;     ...
;         for (int n = 0; n < 2; ++n) { const int c = u.pn * BM + bj * HALF + wc * 32 + (PERM ? 8 * fq + 4 * n : 16 * n + 4 * fq);
;             const f32x4 a1 = *(const GASP f32x4*)(c1 + c), a2 = *(const GASP f32x4*)(c2 + c);
; #pragma unroll
;             for (int ai = 0; ai < 2; ++ai)
; #pragma unroll
;                 for (int m = 0; m < 4; ++m) { const f32x2 st = SL[ai * HALF + wr * 64 + m * 16 + fr]; acc[ai][bj][m][n] = (acc[ai][bj][m][n] - a1 * st[0]) * st[1] + a2; } }
;     __device__ __forceinline__ void operator()(Acc& acc, const Unit& u, int wr, int wc, int fr, int fq, LAS unsigned char* lds) const {
;     ...
;                     f32x4 v0 = acc[ai][bj][m][0], v1 = acc[ai][bj][m][1];
;                     const size_t o = (size_t)row * 512 + col0 + bj * HALF;
;                     if (sec == 0) { v0 = v0 * qscale; v1 = v1 * qscale; }
;                     if (sec == 1) { float* of = (row < NP ? out + OUT_KP + (size_t)row * 512 : out + OUT_KS + (size_t)(row - NP) * 512) + col0 + bj * HALF; __builtin_nontemporal_store(v0, (GASP f32x4*)of); __builtin_nontemporal_store(v1, (GASP f32x4*)(of + 4)); }
;                     if (sec == 2) { float* of = (row < NP ? out + OUT_VP + (size_t)row * 512 : out + OUT_VS + (size_t)(row - NP) * 512) + col0 + bj * HALF; __builtin_nontemporal_store(v0, (GASP f32x4*)of); __builtin_nontemporal_store(v1, (GASP f32x4*)(of + 4)); }
.LBB0_669:
	v_pk_fma_f32 v[80:81], v[60:61], v[94:95], v[80:81] op_sel_hi:[1,0,1] neg_lo:[1,0,0] neg_hi:[1,0,0]
	v_pk_fma_f32 v[82:83], v[198:199], v[94:95], v[82:83] op_sel_hi:[1,0,1]
	v_pk_fma_f32 v[76:77], v[94:95], v[52:53], v[76:77] op_sel_hi:[0,1,1] neg_lo:[1,0,0] neg_hi:[1,0,0]
	v_pk_fma_f32 v[78:79], v[94:95], v[54:55], v[78:79] op_sel_hi:[0,1,1] neg_lo:[1,0,0] neg_hi:[1,0,0]
	v_add_u32_e32 v88, 0x90, v200
	v_pk_fma_f32 v[82:83], v[94:95], v[82:83], v[66:67] op_sel:[1,0,0]
	v_pk_fma_f32 v[80:81], v[94:95], v[80:81], v[64:65] op_sel:[1,0,0]
	v_pk_fma_f32 v[78:79], v[94:95], v[78:79], v[58:59] op_sel:[1,0,0]
	v_pk_fma_f32 v[76:77], v[94:95], v[76:77], v[56:57] op_sel:[1,0,0]
	v_ashrrev_i32_e32 v89, 31, v88
	v_add_u32_e32 v188, 0xffff8090, v200
	v_lshlrev_b64 v[90:91], 9, v[88:89]
	s_movk_i32 s26, 0x7f70
	v_lshlrev_b64 v[84:85], 11, v[188:189]
	s_waitcnt lgkmcnt(0)
	v_pk_mul_f32 v[86:87], v[82:83], s[78:79] op_sel_hi:[1,0]
	v_pk_mul_f32 v[92:93], v[80:81], s[78:79] op_sel_hi:[1,0]
	v_pk_mul_f32 v[96:97], v[78:79], s[78:79] op_sel_hi:[1,0]
	v_pk_mul_f32 v[98:99], v[76:77], s[78:79] op_sel_hi:[1,0]
	v_cmp_gt_i32_e64 s[26:27], s26, v200
	v_cndmask_b32_e64 v81, v81, v93, s[12:13]
	v_cndmask_b32_e64 v80, v80, v92, s[12:13]
	v_cndmask_b32_e64 v83, v83, v87, s[12:13]
	v_cndmask_b32_e64 v82, v82, v86, s[12:13]
	v_cndmask_b32_e64 v77, v77, v99, s[12:13]
	v_cndmask_b32_e64 v76, v76, v98, s[12:13]
	v_cndmask_b32_e64 v79, v79, v97, s[12:13]
	v_cndmask_b32_e64 v78, v78, v96, s[12:13]
	s_and_b64 vcc, exec, s[14:15]
	v_lshl_add_u64 v[92:93], s[72:73], 0, v[84:85]
	v_lshl_add_u64 v[96:97], v[90:91], 2, s[70:71]
	s_cbranch_vccnz .LBB0_675
	v_cndmask_b32_e64 v87, v93, v97, s[26:27]
	v_cndmask_b32_e64 v86, v92, v96, s[26:27]
	v_mov_b32_e32 v63, v189
	v_lshl_add_u64 v[86:87], v[86:87], 0, v[62:63]
	v_mbcnt_lo_u32_b32 v238, -1, 0
	v_mbcnt_hi_u32_b32 v238, -1, v238
	v_bfe_i32 v238, v238, 4, 1
	v_lshlrev_b32_e32 v238, 4, v238
	v_ashrrev_i32_e32 v239, 31, v238
	v_lshl_add_u64 v[236:237], v[86:87], 0, v[238:239]
	v_permlane16_swap_b32_e32 v80, v76
	v_permlane16_swap_b32_e32 v81, v77
	v_permlane16_swap_b32_e32 v82, v78
	v_permlane16_swap_b32_e32 v83, v79
	global_store_dwordx4 v[236:237], v[80:83], off nt
	global_store_dwordx4 v[236:237], v[76:79], off offset:32 nt
	s_nop 1
	v_permlane16_swap_b32_e32 v80, v76
	v_permlane16_swap_b32_e32 v81, v77
	v_permlane16_swap_b32_e32 v82, v78
	v_permlane16_swap_b32_e32 v83, v79
	s_and_b64 vcc, exec, s[16:17]
	v_lshl_add_u64 v[98:99], s[76:77], 0, v[84:85]
	v_lshl_add_u64 v[100:101], v[90:91], 2, s[74:75]
	s_cbranch_vccz .LBB0_676

; #define GASP __attribute__((address_space(1)))
;     __device__ __forceinline__ void operator()(Acc& acc, const Unit& u, int wr, int wc, int fr, int fq, LAS unsigned char* lds) const {
;     ...
;                     f32x4 v0 = acc[ai][bj][m][0], v1 = acc[ai][bj][m][1];
;                     const size_t o = (size_t)row * 512 + col0 + bj * HALF;
;                     if (sec == 0) { v0 = v0 * qscale; v1 = v1 * qscale; }
;                     if (sec == 1) { float* of = (row < NP ? out + OUT_KP + (size_t)row * 512 : out + OUT_KS + (size_t)(row - NP) * 512) + col0 + bj * HALF; __builtin_nontemporal_store(v0, (GASP f32x4*)of); __builtin_nontemporal_store(v1, (GASP f32x4*)(of + 4)); }
;                     if (sec == 2) { float* of = (row < NP ? out + OUT_VP + (size_t)row * 512 : out + OUT_VS + (size_t)(row - NP) * 512) + col0 + bj * HALF; __builtin_nontemporal_store(v0, (GASP f32x4*)of); __builtin_nontemporal_store(v1, (GASP f32x4*)(of + 4)); }
.LBB0_676:
	v_cndmask_b32_e64 v85, v99, v101, s[26:27]
	v_cndmask_b32_e64 v84, v98, v100, s[26:27]
	v_mov_b32_e32 v63, v189
	v_lshl_add_u64 v[84:85], v[84:85], 0, v[62:63]
	v_mbcnt_lo_u32_b32 v238, -1, 0
	v_mbcnt_hi_u32_b32 v238, -1, v238
	v_bfe_i32 v238, v238, 4, 1
	v_lshlrev_b32_e32 v238, 4, v238
	v_ashrrev_i32_e32 v239, 31, v238
	v_lshl_add_u64 v[236:237], v[84:85], 0, v[238:239]
	v_permlane16_swap_b32_e32 v80, v76
	v_permlane16_swap_b32_e32 v81, v77
	v_permlane16_swap_b32_e32 v82, v78
	v_permlane16_swap_b32_e32 v83, v79
	global_store_dwordx4 v[236:237], v[80:83], off nt
	global_store_dwordx4 v[236:237], v[76:79], off offset:32 nt
	s_nop 1
	v_permlane16_swap_b32_e32 v80, v76
	v_permlane16_swap_b32_e32 v81, v77
	v_permlane16_swap_b32_e32 v82, v78
	v_permlane16_swap_b32_e32 v83, v79
	s_and_b64 vcc, exec, s[18:19]
	s_cbranch_vccz .LBB0_672

; #define GASP __attribute__((address_space(1)))
; template <bool PERM>
; __device__ __forceinline__ void ln_fold_fix(Acc& acc, const Unit& u, int wr, int wc, int fr, int fq, const float* c1, const float* c2, LAS unsigned char* lds) {
;     ...
;         for (int n = 0; n < 2; ++n) { const int c = u.pn * BM + bj * HALF + wc * 32 + (PERM ? 8 * fq + 4 * n : 16 * n + 4 * fq);
;             const f32x4 a1 = *(const GASP f32x4*)(c1 + c), a2 = *(const GASP f32x4*)(c2 + c);
; #pragma unroll
;             for (int ai = 0; ai < 2; ++ai)
; #pragma unroll
;                 for (int m = 0; m < 4; ++m) { const f32x2 st = SL[ai * HALF + wr * 64 + m * 16 + fr]; acc[ai][bj][m][n] = (acc[ai][bj][m][n] - a1 * st[0]) * st[1] + a2; } }
;     __device__ __forceinline__ void operator()(Acc& acc, const Unit& u, int wr, int wc, int fr, int fq, LAS unsigned char* lds) const {
;     ...
;                     f32x4 v0 = acc[ai][bj][m][0], v1 = acc[ai][bj][m][1];
;                     const size_t o = (size_t)row * 512 + col0 + bj * HALF;
;                     if (sec == 0) { v0 = v0 * qscale; v1 = v1 * qscale; }
;                     if (sec == 1) { float* of = (row < NP ? out + OUT_KP + (size_t)row * 512 : out + OUT_KS + (size_t)(row - NP) * 512) + col0 + bj * HALF; __builtin_nontemporal_store(v0, (GASP f32x4*)of); __builtin_nontemporal_store(v1, (GASP f32x4*)(of + 4)); }
;                     if (sec == 2) { float* of = (row < NP ? out + OUT_VP + (size_t)row * 512 : out + OUT_VS + (size_t)(row - NP) * 512) + col0 + bj * HALF; __builtin_nontemporal_store(v0, (GASP f32x4*)of); __builtin_nontemporal_store(v1, (GASP f32x4*)(of + 4)); }
.LBB0_692:
	v_xor_b32_e32 v82, 0x80000000, v94
	v_mov_b32_e32 v76, v94
	v_mov_b32_e32 v77, v94
	v_mov_b32_e32 v83, v82
	v_mov_b32_e32 v78, v95
	v_mov_b32_e32 v79, v95
	v_pk_fma_f32 v[72:73], v[76:77], v[36:37], v[72:73] neg_lo:[1,0,0] neg_hi:[1,0,0]
	v_pk_fma_f32 v[74:75], v[82:83], v[38:39], v[74:75]
	v_mov_b32_e32 v94, v95
	v_pk_fma_f32 v[68:69], v[76:77], v[40:41], v[68:69] neg_lo:[1,0,0] neg_hi:[1,0,0]
	v_pk_fma_f32 v[70:71], v[82:83], v[42:43], v[70:71]
	v_pk_fma_f32 v[74:75], v[94:95], v[74:75], v[34:35]
	v_pk_fma_f32 v[72:73], v[78:79], v[72:73], v[32:33]
	v_pk_fma_f32 v[70:71], v[94:95], v[70:71], v[30:31]
	v_pk_fma_f32 v[68:69], v[78:79], v[68:69], v[28:29]
	v_pk_mul_f32 v[76:77], v[74:75], s[78:79] op_sel_hi:[1,0]
	v_pk_mul_f32 v[78:79], v[72:73], s[78:79] op_sel_hi:[1,0]
	v_pk_mul_f32 v[82:83], v[70:71], s[78:79] op_sel_hi:[1,0]
	v_pk_mul_f32 v[84:85], v[68:69], s[78:79] op_sel_hi:[1,0]
	v_cndmask_b32_e64 v73, v73, v79, s[12:13]
	v_cndmask_b32_e64 v72, v72, v78, s[12:13]
	v_cndmask_b32_e64 v75, v75, v77, s[12:13]
	v_cndmask_b32_e64 v74, v74, v76, s[12:13]
	v_cndmask_b32_e64 v69, v69, v85, s[12:13]
	v_cndmask_b32_e64 v68, v68, v84, s[12:13]
	v_cndmask_b32_e64 v71, v71, v83, s[12:13]
	s_and_b64 vcc, exec, s[14:15]
	v_cndmask_b32_e64 v70, v70, v82, s[12:13]
	s_cbranch_vccnz .LBB0_698
	v_cndmask_b32_e64 v77, v93, v97, s[26:27]
	v_cndmask_b32_e64 v76, v92, v96, s[26:27]
	v_mov_b32_e32 v63, v189
	v_lshl_add_u64 v[76:77], v[76:77], 0, v[62:63]
	v_mbcnt_lo_u32_b32 v238, -1, 0
	v_mbcnt_hi_u32_b32 v238, -1, v238
	v_bfe_i32 v238, v238, 4, 1
	v_lshlrev_b32_e32 v238, 4, v238
	v_ashrrev_i32_e32 v239, 31, v238
	v_lshl_add_u64 v[236:237], v[76:77], 0, v[238:239]
	v_permlane16_swap_b32_e32 v72, v68
	v_permlane16_swap_b32_e32 v73, v69
	v_permlane16_swap_b32_e32 v74, v70
	v_permlane16_swap_b32_e32 v75, v71
	global_store_dwordx4 v[236:237], v[72:75], off offset:512 nt
	global_store_dwordx4 v[236:237], v[68:71], off offset:544 nt
	s_nop 1
	v_permlane16_swap_b32_e32 v72, v68
	v_permlane16_swap_b32_e32 v73, v69
	v_permlane16_swap_b32_e32 v74, v70
	v_permlane16_swap_b32_e32 v75, v71
	s_and_b64 vcc, exec, s[16:17]
	s_cbranch_vccz .LBB0_699

; #define GASP __attribute__((address_space(1)))
;     __device__ __forceinline__ void operator()(Acc& acc, const Unit& u, int wr, int wc, int fr, int fq, LAS unsigned char* lds) const {
;     ...
;                     f32x4 v0 = acc[ai][bj][m][0], v1 = acc[ai][bj][m][1];
;                     const size_t o = (size_t)row * 512 + col0 + bj * HALF;
;                     if (sec == 0) { v0 = v0 * qscale; v1 = v1 * qscale; }
;                     if (sec == 1) { float* of = (row < NP ? out + OUT_KP + (size_t)row * 512 : out + OUT_KS + (size_t)(row - NP) * 512) + col0 + bj * HALF; __builtin_nontemporal_store(v0, (GASP f32x4*)of); __builtin_nontemporal_store(v1, (GASP f32x4*)(of + 4)); }
;                     if (sec == 2) { float* of = (row < NP ? out + OUT_VP + (size_t)row * 512 : out + OUT_VS + (size_t)(row - NP) * 512) + col0 + bj * HALF; __builtin_nontemporal_store(v0, (GASP f32x4*)of); __builtin_nontemporal_store(v1, (GASP f32x4*)(of + 4)); }
.LBB0_699:
	v_cndmask_b32_e64 v77, v99, v101, s[26:27]
	v_cndmask_b32_e64 v76, v98, v100, s[26:27]
	v_mov_b32_e32 v63, v189
	v_lshl_add_u64 v[76:77], v[76:77], 0, v[62:63]
	v_mbcnt_lo_u32_b32 v238, -1, 0
	v_mbcnt_hi_u32_b32 v238, -1, v238
	v_bfe_i32 v238, v238, 4, 1
	v_lshlrev_b32_e32 v238, 4, v238
	v_ashrrev_i32_e32 v239, 31, v238
	v_lshl_add_u64 v[236:237], v[76:77], 0, v[238:239]
	v_permlane16_swap_b32_e32 v72, v68
	v_permlane16_swap_b32_e32 v73, v69
	v_permlane16_swap_b32_e32 v74, v70
	v_permlane16_swap_b32_e32 v75, v71
	global_store_dwordx4 v[236:237], v[72:75], off offset:512 nt
	global_store_dwordx4 v[236:237], v[68:71], off offset:544 nt
	s_nop 1
	v_permlane16_swap_b32_e32 v72, v68
	v_permlane16_swap_b32_e32 v73, v69
	v_permlane16_swap_b32_e32 v74, v70
	v_permlane16_swap_b32_e32 v75, v71
	s_and_b64 vcc, exec, s[18:19]
	s_cbranch_vccz .LBB0_695

; #define GASP __attribute__((address_space(1)))
; template <bool PERM>
; __device__ __forceinline__ void ln_fold_fix(Acc& acc, const Unit& u, int wr, int wc, int fr, int fq, const float* c1, const float* c2, LAS unsigned char* lds) {
;     ...
;         for (int n = 0; n < 2; ++n) { const int c = u.pn * BM + bj * HALF + wc * 32 + (PERM ? 8 * fq + 4 * n : 16 * n + 4 * fq);
;             const f32x4 a1 = *(const GASP f32x4*)(c1 + c), a2 = *(const GASP f32x4*)(c2 + c);
; #pragma unroll
;             for (int ai = 0; ai < 2; ++ai)
; #pragma unroll
;                 for (int m = 0; m < 4; ++m) { const f32x2 st = SL[ai * HALF + wr * 64 + m * 16 + fr]; acc[ai][bj][m][n] = (acc[ai][bj][m][n] - a1 * st[0]) * st[1] + a2; } }
;     __device__ __forceinline__ void operator()(Acc& acc, const Unit& u, int wr, int wc, int fr, int fq, LAS unsigned char* lds) const {
;     ...
;                     f32x4 v0 = acc[ai][bj][m][0], v1 = acc[ai][bj][m][1];
;                     const size_t o = (size_t)row * 512 + col0 + bj * HALF;
;                     if (sec == 0) { v0 = v0 * qscale; v1 = v1 * qscale; }
;                     if (sec == 1) { float* of = (row < NP ? out + OUT_KP + (size_t)row * 512 : out + OUT_KS + (size_t)(row - NP) * 512) + col0 + bj * HALF; __builtin_nontemporal_store(v0, (GASP f32x4*)of); __builtin_nontemporal_store(v1, (GASP f32x4*)(of + 4)); }
;                     if (sec == 2) { float* of = (row < NP ? out + OUT_VP + (size_t)row * 512 : out + OUT_VS + (size_t)(row - NP) * 512) + col0 + bj * HALF; __builtin_nontemporal_store(v0, (GASP f32x4*)of); __builtin_nontemporal_store(v1, (GASP f32x4*)(of + 4)); }
.LBB0_718:
	v_pk_fma_f32 v[48:49], v[60:61], v[24:25], v[48:49] op_sel_hi:[1,0,1] neg_lo:[1,0,0] neg_hi:[1,0,0]
	v_pk_fma_f32 v[50:51], v[198:199], v[24:25], v[50:51] op_sel_hi:[1,0,1]
	v_pk_fma_f32 v[44:45], v[24:25], v[52:53], v[44:45] op_sel_hi:[0,1,1] neg_lo:[1,0,0] neg_hi:[1,0,0]
	v_pk_fma_f32 v[46:47], v[24:25], v[54:55], v[46:47] op_sel_hi:[0,1,1] neg_lo:[1,0,0] neg_hi:[1,0,0]
	v_add_u32_e32 v72, 0xa0, v200
	v_pk_fma_f32 v[50:51], v[24:25], v[50:51], v[66:67] op_sel:[1,0,0]
	v_pk_fma_f32 v[48:49], v[24:25], v[48:49], v[64:65] op_sel:[1,0,0]
	v_pk_fma_f32 v[46:47], v[24:25], v[46:47], v[58:59] op_sel:[1,0,0]
	v_pk_fma_f32 v[44:45], v[24:25], v[44:45], v[56:57] op_sel:[1,0,0]
	v_ashrrev_i32_e32 v73, 31, v72
	v_add_u32_e32 v188, 0xffff80a0, v200
	v_lshlrev_b64 v[74:75], 9, v[72:73]
	s_movk_i32 s26, 0x7f60
	v_lshlrev_b64 v[68:69], 11, v[188:189]
	s_waitcnt lgkmcnt(0)
	v_pk_mul_f32 v[70:71], v[50:51], s[78:79] op_sel_hi:[1,0]
	v_pk_mul_f32 v[76:77], v[48:49], s[78:79] op_sel_hi:[1,0]
	v_pk_mul_f32 v[78:79], v[46:47], s[78:79] op_sel_hi:[1,0]
	v_pk_mul_f32 v[80:81], v[44:45], s[78:79] op_sel_hi:[1,0]
	v_cmp_gt_i32_e64 s[26:27], s26, v200
	v_cndmask_b32_e64 v49, v49, v77, s[12:13]
	v_cndmask_b32_e64 v48, v48, v76, s[12:13]
	v_cndmask_b32_e64 v51, v51, v71, s[12:13]
	v_cndmask_b32_e64 v50, v50, v70, s[12:13]
	v_cndmask_b32_e64 v45, v45, v81, s[12:13]
	v_cndmask_b32_e64 v44, v44, v80, s[12:13]
	v_cndmask_b32_e64 v47, v47, v79, s[12:13]
	v_cndmask_b32_e64 v46, v46, v78, s[12:13]
	s_and_b64 vcc, exec, s[14:15]
	v_lshl_add_u64 v[76:77], s[72:73], 0, v[68:69]
	v_lshl_add_u64 v[78:79], v[74:75], 2, s[70:71]
	s_cbranch_vccnz .LBB0_724
	v_cndmask_b32_e64 v71, v77, v79, s[26:27]
	v_cndmask_b32_e64 v70, v76, v78, s[26:27]
	v_mov_b32_e32 v63, v189
	v_lshl_add_u64 v[70:71], v[70:71], 0, v[62:63]
	v_mbcnt_lo_u32_b32 v238, -1, 0
	v_mbcnt_hi_u32_b32 v238, -1, v238
	v_bfe_i32 v238, v238, 4, 1
	v_lshlrev_b32_e32 v238, 4, v238
	v_ashrrev_i32_e32 v239, 31, v238
	v_lshl_add_u64 v[236:237], v[70:71], 0, v[238:239]
	v_permlane16_swap_b32_e32 v48, v44
	v_permlane16_swap_b32_e32 v49, v45
	v_permlane16_swap_b32_e32 v50, v46
	v_permlane16_swap_b32_e32 v51, v47
	global_store_dwordx4 v[236:237], v[48:51], off nt
	global_store_dwordx4 v[236:237], v[44:47], off offset:32 nt
	s_nop 1
	v_permlane16_swap_b32_e32 v48, v44
	v_permlane16_swap_b32_e32 v49, v45
	v_permlane16_swap_b32_e32 v50, v46
	v_permlane16_swap_b32_e32 v51, v47
	s_and_b64 vcc, exec, s[16:17]
	v_lshl_add_u64 v[80:81], s[76:77], 0, v[68:69]
	v_lshl_add_u64 v[82:83], v[74:75], 2, s[74:75]
	s_cbranch_vccz .LBB0_725

; #define GASP __attribute__((address_space(1)))
;     __device__ __forceinline__ void operator()(Acc& acc, const Unit& u, int wr, int wc, int fr, int fq, LAS unsigned char* lds) const {
;     ...
;                     f32x4 v0 = acc[ai][bj][m][0], v1 = acc[ai][bj][m][1];
;                     const size_t o = (size_t)row * 512 + col0 + bj * HALF;
;                     if (sec == 0) { v0 = v0 * qscale; v1 = v1 * qscale; }
;                     if (sec == 1) { float* of = (row < NP ? out + OUT_KP + (size_t)row * 512 : out + OUT_KS + (size_t)(row - NP) * 512) + col0 + bj * HALF; __builtin_nontemporal_store(v0, (GASP f32x4*)of); __builtin_nontemporal_store(v1, (GASP f32x4*)(of + 4)); }
;                     if (sec == 2) { float* of = (row < NP ? out + OUT_VP + (size_t)row * 512 : out + OUT_VS + (size_t)(row - NP) * 512) + col0 + bj * HALF; __builtin_nontemporal_store(v0, (GASP f32x4*)of); __builtin_nontemporal_store(v1, (GASP f32x4*)(of + 4)); }
.LBB0_725:
	v_cndmask_b32_e64 v69, v81, v83, s[26:27]
	v_cndmask_b32_e64 v68, v80, v82, s[26:27]
	v_mov_b32_e32 v63, v189
	v_lshl_add_u64 v[68:69], v[68:69], 0, v[62:63]
	v_mbcnt_lo_u32_b32 v238, -1, 0
	v_mbcnt_hi_u32_b32 v238, -1, v238
	v_bfe_i32 v238, v238, 4, 1
	v_lshlrev_b32_e32 v238, 4, v238
	v_ashrrev_i32_e32 v239, 31, v238
	v_lshl_add_u64 v[236:237], v[68:69], 0, v[238:239]
	v_permlane16_swap_b32_e32 v48, v44
	v_permlane16_swap_b32_e32 v49, v45
	v_permlane16_swap_b32_e32 v50, v46
	v_permlane16_swap_b32_e32 v51, v47
	global_store_dwordx4 v[236:237], v[48:51], off nt
	global_store_dwordx4 v[236:237], v[44:47], off offset:32 nt
	s_nop 1
	v_permlane16_swap_b32_e32 v48, v44
	v_permlane16_swap_b32_e32 v49, v45
	v_permlane16_swap_b32_e32 v50, v46
	v_permlane16_swap_b32_e32 v51, v47
	s_and_b64 vcc, exec, s[18:19]
	s_cbranch_vccz .LBB0_721

; #define GASP __attribute__((address_space(1)))
; template <bool PERM>
; __device__ __forceinline__ void ln_fold_fix(Acc& acc, const Unit& u, int wr, int wc, int fr, int fq, const float* c1, const float* c2, LAS unsigned char* lds) {
;     ...
;         for (int n = 0; n < 2; ++n) { const int c = u.pn * BM + bj * HALF + wc * 32 + (PERM ? 8 * fq + 4 * n : 16 * n + 4 * fq);
;             const f32x4 a1 = *(const GASP f32x4*)(c1 + c), a2 = *(const GASP f32x4*)(c2 + c);
; #pragma unroll
;             for (int ai = 0; ai < 2; ++ai)
; #pragma unroll
;                 for (int m = 0; m < 4; ++m) { const f32x2 st = SL[ai * HALF + wr * 64 + m * 16 + fr]; acc[ai][bj][m][n] = (acc[ai][bj][m][n] - a1 * st[0]) * st[1] + a2; } }
;     __device__ __forceinline__ void operator()(Acc& acc, const Unit& u, int wr, int wc, int fr, int fq, LAS unsigned char* lds) const {
;     ...
;                     f32x4 v0 = acc[ai][bj][m][0], v1 = acc[ai][bj][m][1];
;                     const size_t o = (size_t)row * 512 + col0 + bj * HALF;
;                     if (sec == 0) { v0 = v0 * qscale; v1 = v1 * qscale; }
;                     if (sec == 1) { float* of = (row < NP ? out + OUT_KP + (size_t)row * 512 : out + OUT_KS + (size_t)(row - NP) * 512) + col0 + bj * HALF; __builtin_nontemporal_store(v0, (GASP f32x4*)of); __builtin_nontemporal_store(v1, (GASP f32x4*)(of + 4)); }
;                     if (sec == 2) { float* of = (row < NP ? out + OUT_VP + (size_t)row * 512 : out + OUT_VS + (size_t)(row - NP) * 512) + col0 + bj * HALF; __builtin_nontemporal_store(v0, (GASP f32x4*)of); __builtin_nontemporal_store(v1, (GASP f32x4*)(of + 4)); }
.LBB0_741:
	v_xor_b32_e32 v50, 0x80000000, v24
	v_mov_b32_e32 v44, v24
	v_mov_b32_e32 v45, v24
	v_mov_b32_e32 v51, v50
	v_mov_b32_e32 v46, v25
	v_mov_b32_e32 v47, v25
	v_pk_fma_f32 v[20:21], v[44:45], v[36:37], v[20:21] neg_lo:[1,0,0] neg_hi:[1,0,0]
	v_pk_fma_f32 v[22:23], v[50:51], v[38:39], v[22:23]
	v_mov_b32_e32 v24, v25
	v_pk_fma_f32 v[16:17], v[44:45], v[40:41], v[16:17] neg_lo:[1,0,0] neg_hi:[1,0,0]
	v_pk_fma_f32 v[18:19], v[50:51], v[42:43], v[18:19]
	v_pk_fma_f32 v[22:23], v[24:25], v[22:23], v[34:35]
	v_pk_fma_f32 v[20:21], v[46:47], v[20:21], v[32:33]
	v_pk_fma_f32 v[18:19], v[24:25], v[18:19], v[30:31]
	v_pk_fma_f32 v[16:17], v[46:47], v[16:17], v[28:29]
	v_pk_mul_f32 v[24:25], v[22:23], s[78:79] op_sel_hi:[1,0]
	v_pk_mul_f32 v[44:45], v[20:21], s[78:79] op_sel_hi:[1,0]
	v_pk_mul_f32 v[46:47], v[18:19], s[78:79] op_sel_hi:[1,0]
	v_pk_mul_f32 v[50:51], v[16:17], s[78:79] op_sel_hi:[1,0]
	v_cndmask_b32_e64 v21, v21, v45, s[12:13]
	v_cndmask_b32_e64 v20, v20, v44, s[12:13]
	v_cndmask_b32_e64 v23, v23, v25, s[12:13]
	v_cndmask_b32_e64 v22, v22, v24, s[12:13]
	v_cndmask_b32_e64 v17, v17, v51, s[12:13]
	v_cndmask_b32_e64 v16, v16, v50, s[12:13]
	v_cndmask_b32_e64 v19, v19, v47, s[12:13]
	s_and_b64 vcc, exec, s[14:15]
	v_cndmask_b32_e64 v18, v18, v46, s[12:13]
	s_cbranch_vccnz .LBB0_747
	v_cndmask_b32_e64 v25, v77, v79, s[26:27]
	v_cndmask_b32_e64 v24, v76, v78, s[26:27]
	v_mov_b32_e32 v63, v189
	v_lshl_add_u64 v[24:25], v[24:25], 0, v[62:63]
	v_mbcnt_lo_u32_b32 v238, -1, 0
	v_mbcnt_hi_u32_b32 v238, -1, v238
	v_bfe_i32 v238, v238, 4, 1
	v_lshlrev_b32_e32 v238, 4, v238
	v_ashrrev_i32_e32 v239, 31, v238
	v_lshl_add_u64 v[236:237], v[24:25], 0, v[238:239]
	v_permlane16_swap_b32_e32 v20, v16
	v_permlane16_swap_b32_e32 v21, v17
	v_permlane16_swap_b32_e32 v22, v18
	v_permlane16_swap_b32_e32 v23, v19
	global_store_dwordx4 v[236:237], v[20:23], off offset:512 nt
	global_store_dwordx4 v[236:237], v[16:19], off offset:544 nt
	s_nop 1
	v_permlane16_swap_b32_e32 v20, v16
	v_permlane16_swap_b32_e32 v21, v17
	v_permlane16_swap_b32_e32 v22, v18
	v_permlane16_swap_b32_e32 v23, v19
	s_and_b64 vcc, exec, s[16:17]
	s_cbranch_vccz .LBB0_748

; #define GASP __attribute__((address_space(1)))
;     __device__ __forceinline__ void operator()(Acc& acc, const Unit& u, int wr, int wc, int fr, int fq, LAS unsigned char* lds) const {
;     ...
;                     f32x4 v0 = acc[ai][bj][m][0], v1 = acc[ai][bj][m][1];
;                     const size_t o = (size_t)row * 512 + col0 + bj * HALF;
;                     if (sec == 0) { v0 = v0 * qscale; v1 = v1 * qscale; }
;                     if (sec == 1) { float* of = (row < NP ? out + OUT_KP + (size_t)row * 512 : out + OUT_KS + (size_t)(row - NP) * 512) + col0 + bj * HALF; __builtin_nontemporal_store(v0, (GASP f32x4*)of); __builtin_nontemporal_store(v1, (GASP f32x4*)(of + 4)); }
;                     if (sec == 2) { float* of = (row < NP ? out + OUT_VP + (size_t)row * 512 : out + OUT_VS + (size_t)(row - NP) * 512) + col0 + bj * HALF; __builtin_nontemporal_store(v0, (GASP f32x4*)of); __builtin_nontemporal_store(v1, (GASP f32x4*)(of + 4)); }
.LBB0_748:
	v_cndmask_b32_e64 v25, v81, v83, s[26:27]
	v_cndmask_b32_e64 v24, v80, v82, s[26:27]
	v_mov_b32_e32 v63, v189
	v_lshl_add_u64 v[24:25], v[24:25], 0, v[62:63]
	v_mbcnt_lo_u32_b32 v238, -1, 0
	v_mbcnt_hi_u32_b32 v238, -1, v238
	v_bfe_i32 v238, v238, 4, 1
	v_lshlrev_b32_e32 v238, 4, v238
	v_ashrrev_i32_e32 v239, 31, v238
	v_lshl_add_u64 v[236:237], v[24:25], 0, v[238:239]
	v_permlane16_swap_b32_e32 v20, v16
	v_permlane16_swap_b32_e32 v21, v17
	v_permlane16_swap_b32_e32 v22, v18
	v_permlane16_swap_b32_e32 v23, v19
	global_store_dwordx4 v[236:237], v[20:23], off offset:512 nt
	global_store_dwordx4 v[236:237], v[16:19], off offset:544 nt
	s_nop 1
	v_permlane16_swap_b32_e32 v20, v16
	v_permlane16_swap_b32_e32 v21, v17
	v_permlane16_swap_b32_e32 v22, v18
	v_permlane16_swap_b32_e32 v23, v19
	s_and_b64 vcc, exec, s[18:19]
	s_cbranch_vccz .LBB0_744

; #define GASP __attribute__((address_space(1)))
; template <bool PERM>
; __device__ __forceinline__ void ln_fold_fix(Acc& acc, const Unit& u, int wr, int wc, int fr, int fq, const float* c1, const float* c2, LAS unsigned char* lds) {
;     ...
;         for (int n = 0; n < 2; ++n) { const int c = u.pn * BM + bj * HALF + wc * 32 + (PERM ? 8 * fq + 4 * n : 16 * n + 4 * fq);
;             const f32x4 a1 = *(const GASP f32x4*)(c1 + c), a2 = *(const GASP f32x4*)(c2 + c);
; #pragma unroll
;             for (int ai = 0; ai < 2; ++ai)
; #pragma unroll
;                 for (int m = 0; m < 4; ++m) { const f32x2 st = SL[ai * HALF + wr * 64 + m * 16 + fr]; acc[ai][bj][m][n] = (acc[ai][bj][m][n] - a1 * st[0]) * st[1] + a2; } }
;     __device__ __forceinline__ void operator()(Acc& acc, const Unit& u, int wr, int wc, int fr, int fq, LAS unsigned char* lds) const {
;     ...
;                     f32x4 v0 = acc[ai][bj][m][0], v1 = acc[ai][bj][m][1];
;                     const size_t o = (size_t)row * 512 + col0 + bj * HALF;
;                     if (sec == 0) { v0 = v0 * qscale; v1 = v1 * qscale; }
;                     if (sec == 1) { float* of = (row < NP ? out + OUT_KP + (size_t)row * 512 : out + OUT_KS + (size_t)(row - NP) * 512) + col0 + bj * HALF; __builtin_nontemporal_store(v0, (GASP f32x4*)of); __builtin_nontemporal_store(v1, (GASP f32x4*)(of + 4)); }
;                     if (sec == 2) { float* of = (row < NP ? out + OUT_VP + (size_t)row * 512 : out + OUT_VS + (size_t)(row - NP) * 512) + col0 + bj * HALF; __builtin_nontemporal_store(v0, (GASP f32x4*)of); __builtin_nontemporal_store(v1, (GASP f32x4*)(of + 4)); }
.LBB0_767:
	v_pk_fma_f32 v[12:13], v[60:61], v[26:27], v[12:13] op_sel_hi:[1,0,1] neg_lo:[1,0,0] neg_hi:[1,0,0]
	v_pk_fma_f32 v[14:15], v[198:199], v[26:27], v[14:15] op_sel_hi:[1,0,1]
	v_pk_fma_f32 v[8:9], v[26:27], v[52:53], v[8:9] op_sel_hi:[0,1,1] neg_lo:[1,0,0] neg_hi:[1,0,0]
	v_pk_fma_f32 v[10:11], v[26:27], v[54:55], v[10:11] op_sel_hi:[0,1,1] neg_lo:[1,0,0] neg_hi:[1,0,0]
	v_add_u32_e32 v20, 0xb0, v200
	v_pk_fma_f32 v[14:15], v[26:27], v[14:15], v[66:67] op_sel:[1,0,0]
	v_pk_fma_f32 v[12:13], v[26:27], v[12:13], v[64:65] op_sel:[1,0,0]
	v_pk_fma_f32 v[10:11], v[26:27], v[10:11], v[58:59] op_sel:[1,0,0]
	v_pk_fma_f32 v[8:9], v[26:27], v[8:9], v[56:57] op_sel:[1,0,0]
	v_ashrrev_i32_e32 v21, 31, v20
	v_add_u32_e32 v188, 0xffff80b0, v200
	v_lshlrev_b64 v[22:23], 9, v[20:21]
	s_movk_i32 s26, 0x7f50
	v_lshlrev_b64 v[16:17], 11, v[188:189]
	s_waitcnt lgkmcnt(0)
	v_pk_mul_f32 v[18:19], v[14:15], s[78:79] op_sel_hi:[1,0]
	v_pk_mul_f32 v[24:25], v[12:13], s[78:79] op_sel_hi:[1,0]
	v_pk_mul_f32 v[44:45], v[10:11], s[78:79] op_sel_hi:[1,0]
	v_pk_mul_f32 v[46:47], v[8:9], s[78:79] op_sel_hi:[1,0]
	v_cmp_gt_i32_e64 s[26:27], s26, v200
	v_cndmask_b32_e64 v13, v13, v25, s[12:13]
	v_cndmask_b32_e64 v12, v12, v24, s[12:13]
	v_cndmask_b32_e64 v15, v15, v19, s[12:13]
	v_cndmask_b32_e64 v14, v14, v18, s[12:13]
	v_cndmask_b32_e64 v9, v9, v47, s[12:13]
	v_cndmask_b32_e64 v8, v8, v46, s[12:13]
	v_cndmask_b32_e64 v11, v11, v45, s[12:13]
	v_cndmask_b32_e64 v10, v10, v44, s[12:13]
	s_and_b64 vcc, exec, s[14:15]
	v_lshl_add_u64 v[24:25], s[72:73], 0, v[16:17]
	v_lshl_add_u64 v[44:45], v[22:23], 2, s[70:71]
	s_cbranch_vccnz .LBB0_773
	v_cndmask_b32_e64 v19, v25, v45, s[26:27]
	v_cndmask_b32_e64 v18, v24, v44, s[26:27]
	v_mov_b32_e32 v63, v189
	v_lshl_add_u64 v[18:19], v[18:19], 0, v[62:63]
	v_mbcnt_lo_u32_b32 v238, -1, 0
	v_mbcnt_hi_u32_b32 v238, -1, v238
	v_bfe_i32 v238, v238, 4, 1
	v_lshlrev_b32_e32 v238, 4, v238
	v_ashrrev_i32_e32 v239, 31, v238
	v_lshl_add_u64 v[236:237], v[18:19], 0, v[238:239]
	v_permlane16_swap_b32_e32 v12, v8
	v_permlane16_swap_b32_e32 v13, v9
	v_permlane16_swap_b32_e32 v14, v10
	v_permlane16_swap_b32_e32 v15, v11
	global_store_dwordx4 v[236:237], v[12:15], off nt
	global_store_dwordx4 v[236:237], v[8:11], off offset:32 nt
	s_nop 1
	v_permlane16_swap_b32_e32 v12, v8
	v_permlane16_swap_b32_e32 v13, v9
	v_permlane16_swap_b32_e32 v14, v10
	v_permlane16_swap_b32_e32 v15, v11
	s_and_b64 vcc, exec, s[16:17]
	v_lshl_add_u64 v[46:47], s[76:77], 0, v[16:17]
	v_lshl_add_u64 v[48:49], v[22:23], 2, s[74:75]
	s_cbranch_vccz .LBB0_774

; #define GASP __attribute__((address_space(1)))
;     __device__ __forceinline__ void operator()(Acc& acc, const Unit& u, int wr, int wc, int fr, int fq, LAS unsigned char* lds) const {
;     ...
;                     f32x4 v0 = acc[ai][bj][m][0], v1 = acc[ai][bj][m][1];
;                     const size_t o = (size_t)row * 512 + col0 + bj * HALF;
;                     if (sec == 0) { v0 = v0 * qscale; v1 = v1 * qscale; }
;                     if (sec == 1) { float* of = (row < NP ? out + OUT_KP + (size_t)row * 512 : out + OUT_KS + (size_t)(row - NP) * 512) + col0 + bj * HALF; __builtin_nontemporal_store(v0, (GASP f32x4*)of); __builtin_nontemporal_store(v1, (GASP f32x4*)(of + 4)); }
;                     if (sec == 2) { float* of = (row < NP ? out + OUT_VP + (size_t)row * 512 : out + OUT_VS + (size_t)(row - NP) * 512) + col0 + bj * HALF; __builtin_nontemporal_store(v0, (GASP f32x4*)of); __builtin_nontemporal_store(v1, (GASP f32x4*)(of + 4)); }
.LBB0_774:
	v_cndmask_b32_e64 v17, v47, v49, s[26:27]
	v_cndmask_b32_e64 v16, v46, v48, s[26:27]
	v_mov_b32_e32 v63, v189
	v_lshl_add_u64 v[16:17], v[16:17], 0, v[62:63]
	v_mbcnt_lo_u32_b32 v238, -1, 0
	v_mbcnt_hi_u32_b32 v238, -1, v238
	v_bfe_i32 v238, v238, 4, 1
	v_lshlrev_b32_e32 v238, 4, v238
	v_ashrrev_i32_e32 v239, 31, v238
	v_lshl_add_u64 v[236:237], v[16:17], 0, v[238:239]
	v_permlane16_swap_b32_e32 v12, v8
	v_permlane16_swap_b32_e32 v13, v9
	v_permlane16_swap_b32_e32 v14, v10
	v_permlane16_swap_b32_e32 v15, v11
	global_store_dwordx4 v[236:237], v[12:15], off nt
	global_store_dwordx4 v[236:237], v[8:11], off offset:32 nt
	s_nop 1
	v_permlane16_swap_b32_e32 v12, v8
	v_permlane16_swap_b32_e32 v13, v9
	v_permlane16_swap_b32_e32 v14, v10
	v_permlane16_swap_b32_e32 v15, v11
	s_and_b64 vcc, exec, s[18:19]
	s_cbranch_vccz .LBB0_770

; #define GASP __attribute__((address_space(1)))
; template <bool PERM>
; __device__ __forceinline__ void ln_fold_fix(Acc& acc, const Unit& u, int wr, int wc, int fr, int fq, const float* c1, const float* c2, LAS unsigned char* lds) {
;     ...
;         for (int n = 0; n < 2; ++n) { const int c = u.pn * BM + bj * HALF + wc * 32 + (PERM ? 8 * fq + 4 * n : 16 * n + 4 * fq);
;             const f32x4 a1 = *(const GASP f32x4*)(c1 + c), a2 = *(const GASP f32x4*)(c2 + c);
; #pragma unroll
;             for (int ai = 0; ai < 2; ++ai)
; #pragma unroll
;                 for (int m = 0; m < 4; ++m) { const f32x2 st = SL[ai * HALF + wr * 64 + m * 16 + fr]; acc[ai][bj][m][n] = (acc[ai][bj][m][n] - a1 * st[0]) * st[1] + a2; } }
;     __device__ __forceinline__ void operator()(Acc& acc, const Unit& u, int wr, int wc, int fr, int fq, LAS unsigned char* lds) const {
;     ...
;                     f32x4 v0 = acc[ai][bj][m][0], v1 = acc[ai][bj][m][1];
;                     const size_t o = (size_t)row * 512 + col0 + bj * HALF;
;                     if (sec == 0) { v0 = v0 * qscale; v1 = v1 * qscale; }
;                     if (sec == 1) { float* of = (row < NP ? out + OUT_KP + (size_t)row * 512 : out + OUT_KS + (size_t)(row - NP) * 512) + col0 + bj * HALF; __builtin_nontemporal_store(v0, (GASP f32x4*)of); __builtin_nontemporal_store(v1, (GASP f32x4*)(of + 4)); }
;                     if (sec == 2) { float* of = (row < NP ? out + OUT_VP + (size_t)row * 512 : out + OUT_VS + (size_t)(row - NP) * 512) + col0 + bj * HALF; __builtin_nontemporal_store(v0, (GASP f32x4*)of); __builtin_nontemporal_store(v1, (GASP f32x4*)(of + 4)); }
.LBB0_790:
	v_xor_b32_e32 v14, 0x80000000, v26
	v_mov_b32_e32 v8, v26
	v_mov_b32_e32 v9, v26
	v_mov_b32_e32 v15, v14
	v_mov_b32_e32 v10, v27
	v_mov_b32_e32 v11, v27
	v_pk_fma_f32 v[4:5], v[8:9], v[36:37], v[4:5] neg_lo:[1,0,0] neg_hi:[1,0,0]
	v_pk_fma_f32 v[6:7], v[14:15], v[38:39], v[6:7]
	v_mov_b32_e32 v26, v27
	v_pk_fma_f32 v[0:1], v[8:9], v[40:41], v[0:1] neg_lo:[1,0,0] neg_hi:[1,0,0]
	v_pk_fma_f32 v[2:3], v[14:15], v[42:43], v[2:3]
	v_pk_fma_f32 v[6:7], v[26:27], v[6:7], v[34:35]
	v_pk_fma_f32 v[4:5], v[10:11], v[4:5], v[32:33]
	v_pk_fma_f32 v[2:3], v[26:27], v[2:3], v[30:31]
	v_pk_fma_f32 v[0:1], v[10:11], v[0:1], v[28:29]
	v_pk_mul_f32 v[8:9], v[6:7], s[78:79] op_sel_hi:[1,0]
	v_pk_mul_f32 v[10:11], v[4:5], s[78:79] op_sel_hi:[1,0]
	v_pk_mul_f32 v[14:15], v[2:3], s[78:79] op_sel_hi:[1,0]
	v_pk_mul_f32 v[16:17], v[0:1], s[78:79] op_sel_hi:[1,0]
	v_cndmask_b32_e64 v5, v5, v11, s[12:13]
	v_cndmask_b32_e64 v4, v4, v10, s[12:13]
	v_cndmask_b32_e64 v7, v7, v9, s[12:13]
	v_cndmask_b32_e64 v6, v6, v8, s[12:13]
	v_cndmask_b32_e64 v1, v1, v17, s[12:13]
	v_cndmask_b32_e64 v0, v0, v16, s[12:13]
	v_cndmask_b32_e64 v3, v3, v15, s[12:13]
	s_and_b64 vcc, exec, s[14:15]
	v_cndmask_b32_e64 v2, v2, v14, s[12:13]
	s_cbranch_vccnz .LBB0_797
	v_cndmask_b32_e64 v9, v25, v45, s[26:27]
	v_cndmask_b32_e64 v8, v24, v44, s[26:27]
	v_mov_b32_e32 v63, v189
	v_lshl_add_u64 v[8:9], v[8:9], 0, v[62:63]
	v_mbcnt_lo_u32_b32 v238, -1, 0
	v_mbcnt_hi_u32_b32 v238, -1, v238
	v_bfe_i32 v238, v238, 4, 1
	v_lshlrev_b32_e32 v238, 4, v238
	v_ashrrev_i32_e32 v239, 31, v238
	v_lshl_add_u64 v[236:237], v[8:9], 0, v[238:239]
	v_permlane16_swap_b32_e32 v4, v0
	v_permlane16_swap_b32_e32 v5, v1
	v_permlane16_swap_b32_e32 v6, v2
	v_permlane16_swap_b32_e32 v7, v3
	global_store_dwordx4 v[236:237], v[4:7], off offset:512 nt
	global_store_dwordx4 v[236:237], v[0:3], off offset:544 nt
	s_nop 1
	v_permlane16_swap_b32_e32 v4, v0
	v_permlane16_swap_b32_e32 v5, v1
	v_permlane16_swap_b32_e32 v6, v2
	v_permlane16_swap_b32_e32 v7, v3
	s_and_b64 vcc, exec, s[16:17]
	s_cbranch_vccz .LBB0_798

; #define GASP __attribute__((address_space(1)))
;     __device__ __forceinline__ void operator()(Acc& acc, const Unit& u, int wr, int wc, int fr, int fq, LAS unsigned char* lds) const {
;     ...
;                     f32x4 v0 = acc[ai][bj][m][0], v1 = acc[ai][bj][m][1];
;                     const size_t o = (size_t)row * 512 + col0 + bj * HALF;
;                     if (sec == 0) { v0 = v0 * qscale; v1 = v1 * qscale; }
;                     if (sec == 1) { float* of = (row < NP ? out + OUT_KP + (size_t)row * 512 : out + OUT_KS + (size_t)(row - NP) * 512) + col0 + bj * HALF; __builtin_nontemporal_store(v0, (GASP f32x4*)of); __builtin_nontemporal_store(v1, (GASP f32x4*)(of + 4)); }
;                     if (sec == 2) { float* of = (row < NP ? out + OUT_VP + (size_t)row * 512 : out + OUT_VS + (size_t)(row - NP) * 512) + col0 + bj * HALF; __builtin_nontemporal_store(v0, (GASP f32x4*)of); __builtin_nontemporal_store(v1, (GASP f32x4*)(of + 4)); }
.LBB0_798:
	v_cndmask_b32_e64 v9, v47, v49, s[26:27]
	v_cndmask_b32_e64 v8, v46, v48, s[26:27]
	v_mov_b32_e32 v63, v189
	v_lshl_add_u64 v[8:9], v[8:9], 0, v[62:63]
	v_mbcnt_lo_u32_b32 v238, -1, 0
	v_mbcnt_hi_u32_b32 v238, -1, v238
	v_bfe_i32 v238, v238, 4, 1
	v_lshlrev_b32_e32 v238, 4, v238
	v_ashrrev_i32_e32 v239, 31, v238
	v_lshl_add_u64 v[236:237], v[8:9], 0, v[238:239]
	v_permlane16_swap_b32_e32 v4, v0
	v_permlane16_swap_b32_e32 v5, v1
	v_permlane16_swap_b32_e32 v6, v2
	v_permlane16_swap_b32_e32 v7, v3
	global_store_dwordx4 v[236:237], v[4:7], off offset:512 nt
	global_store_dwordx4 v[236:237], v[0:3], off offset:544 nt
	s_nop 1
	v_permlane16_swap_b32_e32 v4, v0
	v_permlane16_swap_b32_e32 v5, v1
	v_permlane16_swap_b32_e32 v6, v2
	v_permlane16_swap_b32_e32 v7, v3
	s_and_b64 vcc, exec, s[18:19]
	s_cbranch_vccz .LBB0_793
